# GEMM K-loops (up, out, gates, in1, down): first iteration of each tile skips the P1/P2 vmcnt waits that only waited for the previous epilogue's stores
# baseline (speedup 1.0000x reference)
; #define PG8_STAGE(bufoff, gbase, voff) do { _Pragma("unroll") for (int _i = 0; _i < 2; ++_i) \
;         __builtin_amdgcn_global_load_lds((const unsigned*)((const char*)(gbase) + (voff)[_i]), (LAS unsigned*)(lds + (bufoff) + ldsw + _i * 8192), 16, 0, 0); } while (0)
; #define PG8_STAGE_A(bufoff, gbase, spf) do { _Pragma("unroll") for (int _i = 0; _i < 2; ++_i) \
;         __builtin_amdgcn_global_load_lds((const unsigned*)((const char*)(gbase) + (Epi::SPECIAL_ROWS && (spf) ? voffS[_i] : voffA[_i])), (LAS unsigned*)(lds + (bufoff) + ldsw + _i * 8192), 16, 0, 0); } while (0)
; #define PG8_LDA(dst, b, h) do { _Pragma("unroll") for (int m = 0; m < 4; ++m) _Pragma("unroll") for (int k = 0; k < 2; ++k) dst[m][k] = *(const LAS bf16x8*)(lds + PG8_SA(b, h) + aoff + m * 2048 + k * 1024); } while (0)
; #define PG8_LDB(dst, b, h) do { _Pragma("unroll") for (int n = 0; n < 2; ++n) _Pragma("unroll") for (int k = 0; k < 2; ++k) dst[n][k] = *(const LAS bf16x8*)(lds + PG8_SB(b, h) + boff + n * 2048 + k * 1024); } while (0)
; #define PG8_WAIT_V(n) asm volatile("s_waitcnt vmcnt(" #n ")" ::: "memory")
; #define PG8_WAIT_L(n) asm volatile("s_waitcnt lgkmcnt(" #n ")" ::: "memory")
; #define PG8_BAR __builtin_amdgcn_s_barrier()
; template <class Epi>
; __device__ __forceinline__ void gemm_phase(LAS unsigned char* lds, const Gemm g, const Sched& S, const Epi& E) {
;     ...
;         for (int t = 0; t < nt; t += 2) {
;             const bool last = (t == nt - 2);
;             const char* a1 = cA + (size_t)((t + 1) & kmask) * kstep;
;             const char* a2 = last ? nA : cA + (size_t)((t + 2) & kmask) * kstep; const char* b2 = last ? nB : cB + (size_t)((t + 2) & kmask) * kstep;
;             const char* a3 = a2 + kstep; const char* b3 = b2 + kstep;
;             const bool sp2 = last ? nsp : csp; const size_t hA2 = last ? nhA : chA;
;             PG8_LDB(B0, 0, 0); PG8_LDB(B1, 0, 1); PG8_SCHED; PG8_LDA(At, 0, 0); PG8_STAGE_A(PG8_SA(1, 1), a1 + chA, csp);
;             PG8_WAIT_V(8); PG8_WAIT_L(0); PG8_BAR; PG8_MMA(0, 0, At, B0); PG8_MMA(0, 1, At, B1); PG8_BAR; PG8_SCHED;
;             PG8_LDA(At, 0, 1); PG8_STAGE(PG8_SB(0, 0), b2, voffB); PG8_STAGE(PG8_SB(0, 1), b2 + hstepB, voffB); PG8_STAGE_A(PG8_SA(0, 0), a2, sp2);
;             PG8_WAIT_V(8); PG8_WAIT_L(0); PG8_BAR; PG8_MMA(1, 0, At, B0); PG8_MMA(1, 1, At, B1); PG8_BAR; PG8_SCHED;
.LBB0_45:
	s_add_u32 s0, s12, s40
	s_addc_u32 s1, s13, s41
	s_add_u32 s22, s0, 0x100
	s_addc_u32 s23, s1, 0
	s_add_u32 s30, s72, s40
	s_addc_u32 s31, s73, s41
	s_cmpk_eq_i32 s40, 0x700
	s_cselect_b64 s[0:1], -1, 0
	s_and_b64 s[18:19], s[0:1], exec
	s_cselect_b32 s23, s8, s23
	s_cselect_b32 s22, s9, s22
	s_cselect_b32 s31, s43, s31
	s_cselect_b32 s30, s65, s30
	s_and_b64 s[0:1], s[38:39], s[0:1]
	v_cndmask_b32_e64 v0, v103, v102, s[0:1]
	v_and_b32_e32 v0, 1, v0
	s_add_i32 s18, 0, 0x10000
	v_cmp_eq_u32_e32 vcc, 1, v0
	v_add_u32_e32 v0, s18, v252
	s_add_i32 s19, 0, 0x14000
	ds_read_b128 v[104:107], v0
	ds_read_b128 v[108:111], v0 offset:1024
	ds_read_b128 v[112:115], v0 offset:2048
	ds_read_b128 v[116:119], v0 offset:3072
	v_add_u32_e32 v0, s19, v252
	ds_read_b128 v[120:123], v0
	ds_read_b128 v[124:127], v0 offset:1024
	ds_read_b128 v[162:165], v0 offset:2048
	ds_read_b128 v[166:169], v0 offset:3072
	s_and_b64 s[0:1], s[0:1], exec
	s_cselect_b32 s54, 0, s17
	s_cselect_b32 s55, s2, s16
	v_lshl_add_u64 v[128:129], v[100:101], 0, s[40:41]
	s_add_i32 m0, s47, 0xc000
	ds_read_b128 v[170:173], v249
	ds_read_b128 v[174:177], v249 offset:1024
	ds_read_b128 v[178:181], v249 offset:2048
	ds_read_b128 v[182:185], v249 offset:3072
	ds_read_b128 v[186:189], v249 offset:4096
	ds_read_b128 v[190:193], v249 offset:5120
	ds_read_b128 v[212:215], v249 offset:6144
	ds_read_b128 v[216:219], v249 offset:7168
	global_load_lds_dwordx4 v[128:129], off
	v_lshl_add_u64 v[128:129], v[98:99], 0, s[40:41]
	s_add_i32 m0, s47, 0xe000
	s_nop 0
	global_load_lds_dwordx4 v[128:129], off
	s_cmp_eq_u32 s40, 0
	s_cbranch_scc1 .Lfi_skip2
	s_waitcnt vmcnt(8)
.Lfi_skip2:
	s_waitcnt lgkmcnt(0)
	s_barrier
	s_setprio 1
	s_waitcnt lgkmcnt(0)
	v_mfma_f32_16x16x32_bf16 v[158:161], v[104:107], v[170:173], v[158:161]
	v_mfma_f32_16x16x32_bf16 v[154:157], v[112:115], v[170:173], v[154:157]
	v_mfma_f32_16x16x32_bf16 v[142:145], v[104:107], v[178:181], v[142:145]
	v_mfma_f32_16x16x32_bf16 v[138:141], v[112:115], v[178:181], v[138:141]
	v_mfma_f32_16x16x32_bf16 v[86:89], v[104:107], v[186:189], v[86:89]
	v_mfma_f32_16x16x32_bf16 v[82:85], v[112:115], v[186:189], v[82:85]
	v_mfma_f32_16x16x32_bf16 v[94:97], v[104:107], v[212:215], v[94:97]
	v_mfma_f32_16x16x32_bf16 v[90:93], v[112:115], v[212:215], v[90:93]
	v_mfma_f32_16x16x32_bf16 v[158:161], v[108:111], v[174:177], v[158:161]
	v_mfma_f32_16x16x32_bf16 v[154:157], v[116:119], v[174:177], v[154:157]
	v_mfma_f32_16x16x32_bf16 v[142:145], v[108:111], v[182:185], v[142:145]
	v_mfma_f32_16x16x32_bf16 v[138:141], v[116:119], v[182:185], v[138:141]
	v_mfma_f32_16x16x32_bf16 v[86:89], v[108:111], v[190:193], v[86:89]
	v_mfma_f32_16x16x32_bf16 v[82:85], v[116:119], v[190:193], v[82:85]
	v_mfma_f32_16x16x32_bf16 v[94:97], v[108:111], v[216:219], v[94:97]
	v_mfma_f32_16x16x32_bf16 v[90:93], v[116:119], v[216:219], v[90:93]
	s_setprio 0
	s_setprio 1
	v_mfma_f32_16x16x32_bf16 v[150:153], v[120:123], v[170:173], v[150:153]
	v_mfma_f32_16x16x32_bf16 v[146:149], v[162:165], v[170:173], v[146:149]
	v_mfma_f32_16x16x32_bf16 v[134:137], v[120:123], v[178:181], v[134:137]
	v_mfma_f32_16x16x32_bf16 v[128:131], v[162:165], v[178:181], v[130:133]
	v_mfma_f32_16x16x32_bf16 v[62:65], v[120:123], v[186:189], v[62:65]
	v_mfma_f32_16x16x32_bf16 v[58:61], v[162:165], v[186:189], v[58:61]
	v_mfma_f32_16x16x32_bf16 v[78:81], v[120:123], v[212:215], v[78:81]
	v_mfma_f32_16x16x32_bf16 v[74:77], v[162:165], v[212:215], v[74:77]
	v_mfma_f32_16x16x32_bf16 v[150:153], v[124:127], v[174:177], v[150:153]
	v_mfma_f32_16x16x32_bf16 v[146:149], v[166:169], v[174:177], v[146:149]
	v_mfma_f32_16x16x32_bf16 v[134:137], v[124:127], v[182:185], v[134:137]
	v_mfma_f32_16x16x32_bf16 v[128:131], v[166:169], v[182:185], v[128:131]
	v_mfma_f32_16x16x32_bf16 v[62:65], v[124:127], v[190:193], v[62:65]
	v_mfma_f32_16x16x32_bf16 v[58:61], v[166:169], v[190:193], v[58:61]
	v_mfma_f32_16x16x32_bf16 v[78:81], v[124:127], v[216:219], v[78:81]
	v_mfma_f32_16x16x32_bf16 v[74:77], v[166:169], v[216:219], v[74:77]
	s_setprio 0
	s_barrier
	s_add_i32 s0, s18, s46
	v_lshl_add_u64 v[204:205], s[30:31], 0, v[208:209]
	s_mov_b32 m0, s0
	ds_read_b128 v[170:173], v249 offset:16384
	ds_read_b128 v[174:177], v249 offset:17408
	ds_read_b128 v[178:181], v249 offset:18432
	ds_read_b128 v[182:185], v249 offset:19456
	ds_read_b128 v[186:189], v249 offset:20480
	ds_read_b128 v[190:193], v249 offset:21504
	ds_read_b128 v[212:215], v249 offset:22528
	ds_read_b128 v[216:219], v249 offset:23552
	global_load_lds_dwordx4 v[204:205], off
	s_add_i32 m0, s0, 0x2000
	s_add_u32 s0, s30, 0x40000
	v_lshl_add_u64 v[220:221], s[30:31], 0, v[210:211]
	s_addc_u32 s1, s31, 0
	s_add_i32 s18, s19, s46
	global_load_lds_dwordx4 v[220:221], off
	v_lshl_add_u64 v[132:133], s[0:1], 0, v[208:209]
	s_mov_b32 m0, s18
	v_cndmask_b32_e32 v0, v208, v197, vcc
	global_load_lds_dwordx4 v[132:133], off
	v_lshl_add_u64 v[132:133], s[0:1], 0, v[210:211]
	s_add_i32 m0, s18, 0x2000
	v_lshl_add_u64 v[228:229], s[22:23], 0, v[0:1]
	global_load_lds_dwordx4 v[132:133], off
	s_mov_b32 m0, s47
	v_cndmask_b32_e32 v132, v210, v223, vcc
	global_load_lds_dwordx4 v0, s[22:23]
	s_mov_b32 m0, s63
	v_mov_b32_e32 v133, v1
	global_load_lds_dwordx4 v132, s[22:23]
	s_cmp_eq_u32 s40, 0
	s_cbranch_scc1 .Lfi_skip1
	s_waitcnt vmcnt(8)
; #define PG8_STAGE_A(bufoff, gbase, spf) do { _Pragma("unroll") for (int _i = 0; _i < 2; ++_i) \
;         __builtin_amdgcn_global_load_lds((const unsigned*)((const char*)(gbase) + (Epi::SPECIAL_ROWS && (spf) ? voffS[_i] : voffA[_i])), (LAS unsigned*)(lds + (bufoff) + ldsw + _i * 8192), 16, 0, 0); } while (0)
; #define PG8_LDA(dst, b, h) do { _Pragma("unroll") for (int m = 0; m < 4; ++m) _Pragma("unroll") for (int k = 0; k < 2; ++k) dst[m][k] = *(const LAS bf16x8*)(lds + PG8_SA(b, h) + aoff + m * 2048 + k * 1024); } while (0)
; #define PG8_LDB(dst, b, h) do { _Pragma("unroll") for (int n = 0; n < 2; ++n) _Pragma("unroll") for (int k = 0; k < 2; ++k) dst[n][k] = *(const LAS bf16x8*)(lds + PG8_SB(b, h) + boff + n * 2048 + k * 1024); } while (0)
; #define PG8_MMA(ai, bj, At, Bt) do { __builtin_amdgcn_s_setprio(1); _Pragma("unroll") for (int m = 0; m < 4; ++m) _Pragma("unroll") for (int n = 0; n < 2; ++n) _Pragma("unroll") for (int k = 0; k < 2; ++k) \
;         acc[ai][bj][m][n] = __builtin_amdgcn_mfma_f32_16x16x32_bf16(Bt[n][k], At[m][k], acc[ai][bj][m][n], 0, 0, 0); __builtin_amdgcn_s_setprio(0); } while (0)
; #define PG8_WAIT_V(n) asm volatile("s_waitcnt vmcnt(" #n ")" ::: "memory")
; #define PG8_WAIT_L(n) asm volatile("s_waitcnt lgkmcnt(" #n ")" ::: "memory")
; #define PG8_BAR __builtin_amdgcn_s_barrier()
; #define PG8_SCHED __builtin_amdgcn_sched_barrier(0)
; template <class Epi>
; __device__ __forceinline__ void gemm_phase(LAS unsigned char* lds, const Gemm g, const Sched& S, const Epi& E) {
;     ...
;             PG8_WAIT_V(8); PG8_WAIT_L(0); PG8_BAR; PG8_MMA(1, 0, At, B0); PG8_MMA(1, 1, At, B1); PG8_BAR; PG8_SCHED;
;             PG8_LDB(B0, 1, 0); PG8_LDB(B1, 1, 1); PG8_SCHED; PG8_LDA(At, 1, 0); PG8_STAGE_A(PG8_SA(0, 1), a2 + hA2, sp2);
;             PG8_WAIT_V(8); PG8_WAIT_L(0); PG8_BAR; PG8_MMA(0, 0, At, B0); PG8_MMA(0, 1, At, B1); PG8_BAR; PG8_SCHED;
.Lfi_skip1:
	s_waitcnt lgkmcnt(0)
	v_lshl_add_u64 v[230:231], s[22:23], 0, v[132:133]
	s_barrier
	s_setprio 1
	s_waitcnt lgkmcnt(0)
	v_mfma_f32_16x16x32_bf16 v[46:49], v[104:107], v[170:173], v[46:49]
	v_mfma_f32_16x16x32_bf16 v[42:45], v[112:115], v[170:173], v[42:45]
	v_mfma_f32_16x16x32_bf16 v[30:33], v[104:107], v[178:181], v[30:33]
	v_mfma_f32_16x16x32_bf16 v[26:29], v[112:115], v[178:181], v[26:29]
	v_mfma_f32_16x16x32_bf16 v[14:17], v[104:107], v[186:189], v[14:17]
	v_mfma_f32_16x16x32_bf16 v[10:13], v[112:115], v[186:189], v[10:13]
	v_mfma_f32_16x16x32_bf16 v[70:73], v[104:107], v[212:215], v[70:73]
	v_mfma_f32_16x16x32_bf16 v[50:53], v[112:115], v[212:215], v[50:53]
	v_mfma_f32_16x16x32_bf16 v[46:49], v[108:111], v[174:177], v[46:49]
	v_mfma_f32_16x16x32_bf16 v[42:45], v[116:119], v[174:177], v[42:45]
	v_mfma_f32_16x16x32_bf16 v[30:33], v[108:111], v[182:185], v[30:33]
	v_mfma_f32_16x16x32_bf16 v[26:29], v[116:119], v[182:185], v[26:29]
	v_mfma_f32_16x16x32_bf16 v[14:17], v[108:111], v[190:193], v[14:17]
	v_mfma_f32_16x16x32_bf16 v[10:13], v[116:119], v[190:193], v[10:13]
	v_mfma_f32_16x16x32_bf16 v[70:73], v[108:111], v[216:219], v[70:73]
	v_mfma_f32_16x16x32_bf16 v[50:53], v[116:119], v[216:219], v[50:53]
	s_setprio 0
	s_setprio 1
	v_mfma_f32_16x16x32_bf16 v[38:41], v[120:123], v[170:173], v[38:41]
	v_mfma_f32_16x16x32_bf16 v[34:37], v[162:165], v[170:173], v[34:37]
	v_mfma_f32_16x16x32_bf16 v[22:25], v[120:123], v[178:181], v[22:25]
	v_mfma_f32_16x16x32_bf16 v[18:21], v[162:165], v[178:181], v[18:21]
	v_mfma_f32_16x16x32_bf16 v[6:9], v[120:123], v[186:189], v[6:9]
	v_mfma_f32_16x16x32_bf16 v[2:5], v[162:165], v[186:189], v[2:5]
	v_mfma_f32_16x16x32_bf16 v[66:69], v[120:123], v[212:215], v[66:69]
	v_mfma_f32_16x16x32_bf16 v[54:57], v[162:165], v[212:215], v[54:57]
	v_mfma_f32_16x16x32_bf16 v[38:41], v[124:127], v[174:177], v[38:41]
	v_mfma_f32_16x16x32_bf16 v[34:37], v[166:169], v[174:177], v[34:37]
	v_mfma_f32_16x16x32_bf16 v[22:25], v[124:127], v[182:185], v[22:25]
	v_mfma_f32_16x16x32_bf16 v[18:21], v[166:169], v[182:185], v[18:21]
	v_mfma_f32_16x16x32_bf16 v[6:9], v[124:127], v[190:193], v[6:9]
	v_mfma_f32_16x16x32_bf16 v[2:5], v[166:169], v[190:193], v[2:5]
	v_mfma_f32_16x16x32_bf16 v[66:69], v[124:127], v[216:219], v[66:69]
	v_mfma_f32_16x16x32_bf16 v[54:57], v[166:169], v[216:219], v[54:57]
	s_setprio 0
	s_barrier
	s_add_i32 s18, 0, 0x18000
	s_add_i32 s19, 0, 0x1c000
	v_add_u32_e32 v116, s18, v252
	v_add_u32_e32 v133, s19, v252
	ds_read_b128 v[104:107], v116
	ds_read_b128 v[108:111], v116 offset:1024
	ds_read_b128 v[112:115], v116 offset:2048
	ds_read_b128 v[116:119], v116 offset:3072
	ds_read_b128 v[120:123], v133
	ds_read_b128 v[124:127], v133 offset:1024
	ds_read_b128 v[162:165], v133 offset:2048
	ds_read_b128 v[166:169], v133 offset:3072
	s_add_u32 s0, s22, s55
	s_addc_u32 s1, s23, s54
	s_mov_b32 m0, s80
	ds_read_b128 v[170:173], v249 offset:32768
	ds_read_b128 v[174:177], v249 offset:33792
	ds_read_b128 v[178:181], v249 offset:34816
	ds_read_b128 v[182:185], v249 offset:35840
	ds_read_b128 v[186:189], v249 offset:36864
	ds_read_b128 v[190:193], v249 offset:37888
	ds_read_b128 v[212:215], v249 offset:38912
	ds_read_b128 v[216:219], v249 offset:39936
	global_load_lds_dwordx4 v0, s[0:1]
	s_mov_b32 m0, s81
	s_nop 0
	global_load_lds_dwordx4 v132, s[0:1]
	s_waitcnt vmcnt(8)
	s_waitcnt lgkmcnt(0)
	s_barrier
	s_setprio 1
	s_waitcnt lgkmcnt(0)
	v_mfma_f32_16x16x32_bf16 v[158:161], v[104:107], v[170:173], v[158:161]
	v_mfma_f32_16x16x32_bf16 v[154:157], v[112:115], v[170:173], v[154:157]
	v_mfma_f32_16x16x32_bf16 v[142:145], v[104:107], v[178:181], v[142:145]
	v_mfma_f32_16x16x32_bf16 v[138:141], v[112:115], v[178:181], v[138:141]
	v_mfma_f32_16x16x32_bf16 v[86:89], v[104:107], v[186:189], v[86:89]
	v_mfma_f32_16x16x32_bf16 v[82:85], v[112:115], v[186:189], v[82:85]
	v_mfma_f32_16x16x32_bf16 v[94:97], v[104:107], v[212:215], v[94:97]
	v_mfma_f32_16x16x32_bf16 v[90:93], v[112:115], v[212:215], v[90:93]
	v_mfma_f32_16x16x32_bf16 v[158:161], v[108:111], v[174:177], v[158:161]
	v_mfma_f32_16x16x32_bf16 v[154:157], v[116:119], v[174:177], v[154:157]
	v_mfma_f32_16x16x32_bf16 v[142:145], v[108:111], v[182:185], v[142:145]
	v_mfma_f32_16x16x32_bf16 v[138:141], v[116:119], v[182:185], v[138:141]
	v_mfma_f32_16x16x32_bf16 v[86:89], v[108:111], v[190:193], v[86:89]
	v_mfma_f32_16x16x32_bf16 v[82:85], v[116:119], v[190:193], v[82:85]
	v_mfma_f32_16x16x32_bf16 v[94:97], v[108:111], v[216:219], v[94:97]
	v_mfma_f32_16x16x32_bf16 v[90:93], v[116:119], v[216:219], v[90:93]
	s_setprio 0
	s_setprio 1
	v_mfma_f32_16x16x32_bf16 v[150:153], v[120:123], v[170:173], v[150:153]
	v_mfma_f32_16x16x32_bf16 v[146:149], v[162:165], v[170:173], v[146:149]
	v_mfma_f32_16x16x32_bf16 v[132:135], v[120:123], v[178:181], v[134:137]
	v_mfma_f32_16x16x32_bf16 v[128:131], v[162:165], v[178:181], v[128:131]
	v_mfma_f32_16x16x32_bf16 v[62:65], v[120:123], v[186:189], v[62:65]
	v_mfma_f32_16x16x32_bf16 v[58:61], v[162:165], v[186:189], v[58:61]
	v_mfma_f32_16x16x32_bf16 v[78:81], v[120:123], v[212:215], v[78:81]
	v_mfma_f32_16x16x32_bf16 v[74:77], v[162:165], v[212:215], v[74:77]
	v_mfma_f32_16x16x32_bf16 v[150:153], v[124:127], v[174:177], v[150:153]
	v_mfma_f32_16x16x32_bf16 v[146:149], v[166:169], v[174:177], v[146:149]
	v_mfma_f32_16x16x32_bf16 v[134:137], v[124:127], v[182:185], v[132:135]
	v_mfma_f32_16x16x32_bf16 v[130:133], v[166:169], v[182:185], v[128:131]
	v_mfma_f32_16x16x32_bf16 v[62:65], v[124:127], v[190:193], v[62:65]
	v_mfma_f32_16x16x32_bf16 v[58:61], v[166:169], v[190:193], v[58:61]
	v_mfma_f32_16x16x32_bf16 v[78:81], v[124:127], v[216:219], v[78:81]
	v_mfma_f32_16x16x32_bf16 v[74:77], v[166:169], v[216:219], v[74:77]
	s_setprio 0
	s_barrier
; #define PG8_STAGE(bufoff, gbase, voff) do { _Pragma("unroll") for (int _i = 0; _i < 2; ++_i) \
;         __builtin_amdgcn_global_load_lds((const unsigned*)((const char*)(gbase) + (voff)[_i]), (LAS unsigned*)(lds + (bufoff) + ldsw + _i * 8192), 16, 0, 0); } while (0)
; #define PG8_STAGE_A(bufoff, gbase, spf) do { _Pragma("unroll") for (int _i = 0; _i < 2; ++_i) \
;         __builtin_amdgcn_global_load_lds((const unsigned*)((const char*)(gbase) + (Epi::SPECIAL_ROWS && (spf) ? voffS[_i] : voffA[_i])), (LAS unsigned*)(lds + (bufoff) + ldsw + _i * 8192), 16, 0, 0); } while (0)
; #define PG8_LDA(dst, b, h) do { _Pragma("unroll") for (int m = 0; m < 4; ++m) _Pragma("unroll") for (int k = 0; k < 2; ++k) dst[m][k] = *(const LAS bf16x8*)(lds + PG8_SA(b, h) + aoff + m * 2048 + k * 1024); } while (0)
; #define PG8_MMA(ai, bj, At, Bt) do { __builtin_amdgcn_s_setprio(1); _Pragma("unroll") for (int m = 0; m < 4; ++m) _Pragma("unroll") for (int n = 0; n < 2; ++n) _Pragma("unroll") for (int k = 0; k < 2; ++k) \
;         acc[ai][bj][m][n] = __builtin_amdgcn_mfma_f32_16x16x32_bf16(Bt[n][k], At[m][k], acc[ai][bj][m][n], 0, 0, 0); __builtin_amdgcn_s_setprio(0); } while (0)
; #define PG8_WAIT_V(n) asm volatile("s_waitcnt vmcnt(" #n ")" ::: "memory")
; #define PG8_WAIT_L(n) asm volatile("s_waitcnt lgkmcnt(" #n ")" ::: "memory")
; #define PG8_BAR __builtin_amdgcn_s_barrier()
; #define PG8_SCHED __builtin_amdgcn_sched_barrier(0)
; template <class Epi>
; __device__ __forceinline__ void gemm_phase(LAS unsigned char* lds, const Gemm g, const Sched& S, const Epi& E) {
;     ...
;             PG8_LDA(At, 1, 1); PG8_STAGE(PG8_SB(1, 0), b3, voffB); PG8_STAGE(PG8_SB(1, 1), b3 + hstepB, voffB); PG8_STAGE_A(PG8_SA(1, 0), a3, sp2);
;             PG8_WAIT_V(8); PG8_WAIT_L(0); PG8_BAR; PG8_MMA(1, 0, At, B0); PG8_MMA(1, 1, At, B1); PG8_BAR; PG8_SCHED;
;         }
;         if (wr == 0) PG8_BAR;
	s_add_i32 s0, s18, s46
	v_lshl_add_u64 v[128:129], v[204:205], 0, s[20:21]
	s_mov_b32 m0, s0
	ds_read_b128 v[170:173], v249 offset:49152
	ds_read_b128 v[174:177], v249 offset:50176
	ds_read_b128 v[178:181], v249 offset:51200
	ds_read_b128 v[182:185], v249 offset:52224
	ds_read_b128 v[186:189], v249 offset:53248
	ds_read_b128 v[190:193], v249 offset:54272
	ds_read_b128 v[212:215], v249 offset:55296
	ds_read_b128 v[216:219], v249 offset:56320
	global_load_lds_dwordx4 v[128:129], off
	s_add_i32 m0, s0, 0x2000
	s_add_u32 s0, s30, 0x40080
	v_lshl_add_u64 v[128:129], v[220:221], 0, s[20:21]
	s_addc_u32 s1, s31, 0
	s_add_i32 s18, s19, s46
	global_load_lds_dwordx4 v[128:129], off
	v_lshl_add_u64 v[128:129], s[0:1], 0, v[208:209]
	s_mov_b32 m0, s18
	s_nop 0
	global_load_lds_dwordx4 v[128:129], off
	v_lshl_add_u64 v[128:129], s[0:1], 0, v[210:211]
	s_add_i32 m0, s18, 0x2000
	s_nop 0
	global_load_lds_dwordx4 v[128:129], off
	v_lshl_add_u64 v[128:129], v[228:229], 0, s[20:21]
	s_mov_b32 m0, s84
	s_nop 0
	global_load_lds_dwordx4 v[128:129], off
	v_lshl_add_u64 v[128:129], v[230:231], 0, s[20:21]
	s_mov_b32 m0, s85
	s_nop 0
	global_load_lds_dwordx4 v[128:129], off
	s_waitcnt vmcnt(8)
	s_waitcnt lgkmcnt(0)
	s_barrier
	s_setprio 1
	s_waitcnt lgkmcnt(0)
	v_mfma_f32_16x16x32_bf16 v[46:49], v[104:107], v[170:173], v[46:49]
	v_mfma_f32_16x16x32_bf16 v[42:45], v[112:115], v[170:173], v[42:45]
	v_mfma_f32_16x16x32_bf16 v[30:33], v[104:107], v[178:181], v[30:33]
	v_mfma_f32_16x16x32_bf16 v[26:29], v[112:115], v[178:181], v[26:29]
	v_mfma_f32_16x16x32_bf16 v[14:17], v[104:107], v[186:189], v[14:17]
	v_mfma_f32_16x16x32_bf16 v[10:13], v[112:115], v[186:189], v[10:13]
	v_mfma_f32_16x16x32_bf16 v[70:73], v[104:107], v[212:215], v[70:73]
	v_mfma_f32_16x16x32_bf16 v[50:53], v[112:115], v[212:215], v[50:53]
	v_mfma_f32_16x16x32_bf16 v[46:49], v[108:111], v[174:177], v[46:49]
	v_mfma_f32_16x16x32_bf16 v[42:45], v[116:119], v[174:177], v[42:45]
	v_mfma_f32_16x16x32_bf16 v[30:33], v[108:111], v[182:185], v[30:33]
	v_mfma_f32_16x16x32_bf16 v[26:29], v[116:119], v[182:185], v[26:29]
	v_mfma_f32_16x16x32_bf16 v[14:17], v[108:111], v[190:193], v[14:17]
	v_mfma_f32_16x16x32_bf16 v[10:13], v[116:119], v[190:193], v[10:13]
	v_mfma_f32_16x16x32_bf16 v[70:73], v[108:111], v[216:219], v[70:73]
	v_mfma_f32_16x16x32_bf16 v[50:53], v[116:119], v[216:219], v[50:53]
	s_setprio 0
	s_setprio 1
	v_mfma_f32_16x16x32_bf16 v[38:41], v[120:123], v[170:173], v[38:41]
	v_mfma_f32_16x16x32_bf16 v[34:37], v[162:165], v[170:173], v[34:37]
	v_mfma_f32_16x16x32_bf16 v[22:25], v[120:123], v[178:181], v[22:25]
	v_mfma_f32_16x16x32_bf16 v[18:21], v[162:165], v[178:181], v[18:21]
	v_mfma_f32_16x16x32_bf16 v[6:9], v[120:123], v[186:189], v[6:9]
	v_mfma_f32_16x16x32_bf16 v[2:5], v[162:165], v[186:189], v[2:5]
	v_mfma_f32_16x16x32_bf16 v[66:69], v[120:123], v[212:215], v[66:69]
	v_mfma_f32_16x16x32_bf16 v[54:57], v[162:165], v[212:215], v[54:57]
	v_mfma_f32_16x16x32_bf16 v[38:41], v[124:127], v[174:177], v[38:41]
	v_mfma_f32_16x16x32_bf16 v[34:37], v[166:169], v[174:177], v[34:37]
	v_mfma_f32_16x16x32_bf16 v[22:25], v[124:127], v[182:185], v[22:25]
	v_mfma_f32_16x16x32_bf16 v[18:21], v[166:169], v[182:185], v[18:21]
	v_mfma_f32_16x16x32_bf16 v[6:9], v[124:127], v[190:193], v[6:9]
	v_mfma_f32_16x16x32_bf16 v[2:5], v[166:169], v[190:193], v[2:5]
	v_mfma_f32_16x16x32_bf16 v[66:69], v[124:127], v[216:219], v[66:69]
	v_mfma_f32_16x16x32_bf16 v[54:57], v[166:169], v[216:219], v[54:57]
	s_setprio 0
	s_barrier
	s_add_i32 s75, s75, 2
	s_add_u32 s40, s40, 0x100
	s_addc_u32 s41, s41, 0
	s_cmp_gt_u32 s75, 13
	s_cbranch_scc0 .LBB0_45
	v_readlane_b32 s0, v255, 31
	v_readlane_b32 s1, v255, 32
	s_and_b64 vcc, exec, s[0:1]
	s_cbranch_vccz .LBB0_48
	s_barrier

; #define PG8_STAGE(bufoff, gbase, voff) do { _Pragma("unroll") for (int _i = 0; _i < 2; ++_i) \
;         __builtin_amdgcn_global_load_lds((const unsigned*)((const char*)(gbase) + (voff)[_i]), (LAS unsigned*)(lds + (bufoff) + ldsw + _i * 8192), 16, 0, 0); } while (0)
; #define PG8_STAGE_A(bufoff, gbase, spf) do { _Pragma("unroll") for (int _i = 0; _i < 2; ++_i) \
;         __builtin_amdgcn_global_load_lds((const unsigned*)((const char*)(gbase) + (Epi::SPECIAL_ROWS && (spf) ? voffS[_i] : voffA[_i])), (LAS unsigned*)(lds + (bufoff) + ldsw + _i * 8192), 16, 0, 0); } while (0)
; #define PG8_LDA(dst, b, h) do { _Pragma("unroll") for (int m = 0; m < 4; ++m) _Pragma("unroll") for (int k = 0; k < 2; ++k) dst[m][k] = *(const LAS bf16x8*)(lds + PG8_SA(b, h) + aoff + m * 2048 + k * 1024); } while (0)
; #define PG8_LDB(dst, b, h) do { _Pragma("unroll") for (int n = 0; n < 2; ++n) _Pragma("unroll") for (int k = 0; k < 2; ++k) dst[n][k] = *(const LAS bf16x8*)(lds + PG8_SB(b, h) + boff + n * 2048 + k * 1024); } while (0)
; #define PG8_WAIT_V(n) asm volatile("s_waitcnt vmcnt(" #n ")" ::: "memory")
; #define PG8_WAIT_L(n) asm volatile("s_waitcnt lgkmcnt(" #n ")" ::: "memory")
; #define PG8_BAR __builtin_amdgcn_s_barrier()
; template <class Epi>
; __device__ __forceinline__ void gemm_phase(LAS unsigned char* lds, const Gemm g, const Sched& S, const Epi& E) {
;     ...
;         for (int t = 0; t < nt; t += 2) {
;             const bool last = (t == nt - 2);
;             const char* a1 = cA + (size_t)((t + 1) & kmask) * kstep;
;             const char* a2 = last ? nA : cA + (size_t)((t + 2) & kmask) * kstep; const char* b2 = last ? nB : cB + (size_t)((t + 2) & kmask) * kstep;
;             const char* a3 = a2 + kstep; const char* b3 = b2 + kstep;
;             const bool sp2 = last ? nsp : csp; const size_t hA2 = last ? nhA : chA;
;             PG8_LDB(B0, 0, 0); PG8_LDB(B1, 0, 1); PG8_SCHED; PG8_LDA(At, 0, 0); PG8_STAGE_A(PG8_SA(1, 1), a1 + chA, csp);
;             PG8_WAIT_V(8); PG8_WAIT_L(0); PG8_BAR; PG8_MMA(0, 0, At, B0); PG8_MMA(0, 1, At, B1); PG8_BAR; PG8_SCHED;
;             PG8_LDA(At, 0, 1); PG8_STAGE(PG8_SB(0, 0), b2, voffB); PG8_STAGE(PG8_SB(0, 1), b2 + hstepB, voffB); PG8_STAGE_A(PG8_SA(0, 0), a2, sp2);
;             PG8_WAIT_V(8); PG8_WAIT_L(0); PG8_BAR; PG8_MMA(1, 0, At, B0); PG8_MMA(1, 1, At, B1); PG8_BAR; PG8_SCHED;
.LBB0_199:
	s_add_u32 s8, s72, 0xfffc0080
	s_addc_u32 s9, s73, -1
	s_add_i32 s18, 0, 0x10000
	s_cmp_eq_u32 s46, 12
	s_cselect_b32 s9, s2, s9
	s_cselect_b32 s8, s13, s8
	s_cselect_b32 s23, s43, s31
	s_cselect_b32 s22, s65, s30
	s_add_i32 s47, 0, 0x14000
	v_add_u32_e32 v142, s18, v197
	v_add_u32_e32 v158, s47, v197
	ds_read_b128 v[130:133], v142
	ds_read_b128 v[134:137], v142 offset:1024
	ds_read_b128 v[138:141], v142 offset:2048
	ds_read_b128 v[142:145], v142 offset:3072
	ds_read_b128 v[146:149], v158
	ds_read_b128 v[150:153], v158 offset:1024
	ds_read_b128 v[154:157], v158 offset:2048
	ds_read_b128 v[158:161], v158 offset:3072
	v_lshl_add_u64 v[216:217], s[72:73], 0, v[212:213]
	s_add_i32 m0, s80, 0xc000
	ds_read_b128 v[162:165], v204
	ds_read_b128 v[166:169], v204 offset:1024
	ds_read_b128 v[170:173], v204 offset:2048
	ds_read_b128 v[174:177], v204 offset:3072
	ds_read_b128 v[178:181], v204 offset:4096
	ds_read_b128 v[182:185], v204 offset:5120
	ds_read_b128 v[186:189], v204 offset:6144
	ds_read_b128 v[190:193], v204 offset:7168
	global_load_lds_dwordx4 v[216:217], off
	v_lshl_add_u64 v[216:217], s[72:73], 0, v[214:215]
	s_add_i32 m0, s80, 0xe000
	s_nop 0
	global_load_lds_dwordx4 v[216:217], off
	s_cmp_eq_i32 s46, -2
	s_cbranch_scc1 .Lfi_skip4
	s_waitcnt vmcnt(8)
.Lfi_skip4:
	s_waitcnt lgkmcnt(0)
	s_barrier
	s_setprio 1
	s_waitcnt lgkmcnt(0)
	v_mfma_f32_16x16x32_bf16 v[126:129], v[130:133], v[162:165], v[126:129]
	v_mfma_f32_16x16x32_bf16 v[122:125], v[138:141], v[162:165], v[122:125]
	v_mfma_f32_16x16x32_bf16 v[110:113], v[130:133], v[170:173], v[110:113]
	v_mfma_f32_16x16x32_bf16 v[106:109], v[138:141], v[170:173], v[106:109]
	v_mfma_f32_16x16x32_bf16 v[94:97], v[130:133], v[178:181], v[94:97]
	v_mfma_f32_16x16x32_bf16 v[90:93], v[138:141], v[178:181], v[90:93]
	v_mfma_f32_16x16x32_bf16 v[78:81], v[130:133], v[186:189], v[78:81]
	v_mfma_f32_16x16x32_bf16 v[74:77], v[138:141], v[186:189], v[74:77]
	v_mfma_f32_16x16x32_bf16 v[126:129], v[134:137], v[166:169], v[126:129]
	v_mfma_f32_16x16x32_bf16 v[122:125], v[142:145], v[166:169], v[122:125]
	v_mfma_f32_16x16x32_bf16 v[110:113], v[134:137], v[174:177], v[110:113]
	v_mfma_f32_16x16x32_bf16 v[106:109], v[142:145], v[174:177], v[106:109]
	v_mfma_f32_16x16x32_bf16 v[94:97], v[134:137], v[182:185], v[94:97]
	v_mfma_f32_16x16x32_bf16 v[90:93], v[142:145], v[182:185], v[90:93]
	v_mfma_f32_16x16x32_bf16 v[78:81], v[134:137], v[190:193], v[78:81]
	v_mfma_f32_16x16x32_bf16 v[74:77], v[142:145], v[190:193], v[74:77]
	s_setprio 0
	s_setprio 1
	v_mfma_f32_16x16x32_bf16 v[118:121], v[146:149], v[162:165], v[118:121]
	v_mfma_f32_16x16x32_bf16 v[114:117], v[154:157], v[162:165], v[114:117]
	v_mfma_f32_16x16x32_bf16 v[102:105], v[146:149], v[170:173], v[102:105]
	v_mfma_f32_16x16x32_bf16 v[98:101], v[154:157], v[170:173], v[98:101]
	v_mfma_f32_16x16x32_bf16 v[86:89], v[146:149], v[178:181], v[86:89]
	v_mfma_f32_16x16x32_bf16 v[82:85], v[154:157], v[178:181], v[82:85]
	v_mfma_f32_16x16x32_bf16 v[70:73], v[146:149], v[186:189], v[70:73]
	v_mfma_f32_16x16x32_bf16 v[66:69], v[154:157], v[186:189], v[66:69]
	v_mfma_f32_16x16x32_bf16 v[118:121], v[150:153], v[166:169], v[118:121]
	v_mfma_f32_16x16x32_bf16 v[114:117], v[158:161], v[166:169], v[114:117]
	v_mfma_f32_16x16x32_bf16 v[102:105], v[150:153], v[174:177], v[102:105]
	v_mfma_f32_16x16x32_bf16 v[98:101], v[158:161], v[174:177], v[98:101]
	v_mfma_f32_16x16x32_bf16 v[86:89], v[150:153], v[182:185], v[86:89]
	v_mfma_f32_16x16x32_bf16 v[82:85], v[158:161], v[182:185], v[82:85]
	v_mfma_f32_16x16x32_bf16 v[70:73], v[150:153], v[190:193], v[70:73]
	v_mfma_f32_16x16x32_bf16 v[66:69], v[158:161], v[190:193], v[66:69]
	s_setprio 0
	s_barrier
	s_add_i32 s18, s18, s36
	v_lshl_add_u64 v[216:217], s[22:23], 0, v[0:1]
	s_mov_b32 m0, s18
	ds_read_b128 v[162:165], v204 offset:16384
	ds_read_b128 v[166:169], v204 offset:17408
	ds_read_b128 v[170:173], v204 offset:18432
	ds_read_b128 v[174:177], v204 offset:19456
	ds_read_b128 v[178:181], v204 offset:20480
	ds_read_b128 v[182:185], v204 offset:21504
	ds_read_b128 v[186:189], v204 offset:22528
	ds_read_b128 v[190:193], v204 offset:23552
	global_load_lds_dwordx4 v[216:217], off
	s_add_i32 m0, s18, 0x2000
	s_add_u32 s18, s22, 0x40000
	v_lshl_add_u64 v[218:219], s[22:23], 0, v[208:209]
	s_addc_u32 s19, s23, 0
	s_add_i32 s47, s47, s36
	global_load_lds_dwordx4 v[218:219], off
	v_lshl_add_u64 v[220:221], s[18:19], 0, v[0:1]
	s_mov_b32 m0, s47
	v_lshl_add_u64 v[222:223], s[8:9], 0, v[208:209]
	global_load_lds_dwordx4 v[220:221], off
	v_lshl_add_u64 v[220:221], s[18:19], 0, v[208:209]
	s_add_i32 m0, s47, 0x2000
	s_nop 0
	global_load_lds_dwordx4 v[220:221], off
	v_lshl_add_u64 v[220:221], s[8:9], 0, v[0:1]
	s_mov_b32 m0, s80
	s_nop 0
	global_load_lds_dwordx4 v[220:221], off
	s_mov_b32 m0, s81
	s_nop 0
	global_load_lds_dwordx4 v[222:223], off
	s_cmp_eq_i32 s46, -2
	s_cbranch_scc1 .Lfi_skip3
	s_waitcnt vmcnt(8)
; #define PG8_STAGE_A(bufoff, gbase, spf) do { _Pragma("unroll") for (int _i = 0; _i < 2; ++_i) \
;         __builtin_amdgcn_global_load_lds((const unsigned*)((const char*)(gbase) + (Epi::SPECIAL_ROWS && (spf) ? voffS[_i] : voffA[_i])), (LAS unsigned*)(lds + (bufoff) + ldsw + _i * 8192), 16, 0, 0); } while (0)
; #define PG8_LDA(dst, b, h) do { _Pragma("unroll") for (int m = 0; m < 4; ++m) _Pragma("unroll") for (int k = 0; k < 2; ++k) dst[m][k] = *(const LAS bf16x8*)(lds + PG8_SA(b, h) + aoff + m * 2048 + k * 1024); } while (0)
; #define PG8_LDB(dst, b, h) do { _Pragma("unroll") for (int n = 0; n < 2; ++n) _Pragma("unroll") for (int k = 0; k < 2; ++k) dst[n][k] = *(const LAS bf16x8*)(lds + PG8_SB(b, h) + boff + n * 2048 + k * 1024); } while (0)
; #define PG8_MMA(ai, bj, At, Bt) do { __builtin_amdgcn_s_setprio(1); _Pragma("unroll") for (int m = 0; m < 4; ++m) _Pragma("unroll") for (int n = 0; n < 2; ++n) _Pragma("unroll") for (int k = 0; k < 2; ++k) \
;         acc[ai][bj][m][n] = __builtin_amdgcn_mfma_f32_16x16x32_bf16(Bt[n][k], At[m][k], acc[ai][bj][m][n], 0, 0, 0); __builtin_amdgcn_s_setprio(0); } while (0)
; #define PG8_WAIT_V(n) asm volatile("s_waitcnt vmcnt(" #n ")" ::: "memory")
; #define PG8_WAIT_L(n) asm volatile("s_waitcnt lgkmcnt(" #n ")" ::: "memory")
; #define PG8_BAR __builtin_amdgcn_s_barrier()
; #define PG8_SCHED __builtin_amdgcn_sched_barrier(0)
; template <class Epi>
; __device__ __forceinline__ void gemm_phase(LAS unsigned char* lds, const Gemm g, const Sched& S, const Epi& E) {
;     ...
;             PG8_WAIT_V(8); PG8_WAIT_L(0); PG8_BAR; PG8_MMA(1, 0, At, B0); PG8_MMA(1, 1, At, B1); PG8_BAR; PG8_SCHED;
;             PG8_LDB(B0, 1, 0); PG8_LDB(B1, 1, 1); PG8_SCHED; PG8_LDA(At, 1, 0); PG8_STAGE_A(PG8_SA(0, 1), a2 + hA2, sp2);
;             PG8_WAIT_V(8); PG8_WAIT_L(0); PG8_BAR; PG8_MMA(0, 0, At, B0); PG8_MMA(0, 1, At, B1); PG8_BAR; PG8_SCHED;
.Lfi_skip3:
	s_waitcnt lgkmcnt(0)
	s_barrier
	s_setprio 1
	s_waitcnt lgkmcnt(0)
	v_mfma_f32_16x16x32_bf16 v[62:65], v[130:133], v[162:165], v[62:65]
	v_mfma_f32_16x16x32_bf16 v[58:61], v[138:141], v[162:165], v[58:61]
	v_mfma_f32_16x16x32_bf16 v[46:49], v[130:133], v[170:173], v[46:49]
	v_mfma_f32_16x16x32_bf16 v[42:45], v[138:141], v[170:173], v[42:45]
	v_mfma_f32_16x16x32_bf16 v[30:33], v[130:133], v[178:181], v[30:33]
	v_mfma_f32_16x16x32_bf16 v[26:29], v[138:141], v[178:181], v[26:29]
	v_mfma_f32_16x16x32_bf16 v[14:17], v[130:133], v[186:189], v[14:17]
	v_mfma_f32_16x16x32_bf16 v[10:13], v[138:141], v[186:189], v[10:13]
	v_mfma_f32_16x16x32_bf16 v[62:65], v[134:137], v[166:169], v[62:65]
	v_mfma_f32_16x16x32_bf16 v[58:61], v[142:145], v[166:169], v[58:61]
	v_mfma_f32_16x16x32_bf16 v[46:49], v[134:137], v[174:177], v[46:49]
	v_mfma_f32_16x16x32_bf16 v[42:45], v[142:145], v[174:177], v[42:45]
	v_mfma_f32_16x16x32_bf16 v[30:33], v[134:137], v[182:185], v[30:33]
	v_mfma_f32_16x16x32_bf16 v[26:29], v[142:145], v[182:185], v[26:29]
	v_mfma_f32_16x16x32_bf16 v[14:17], v[134:137], v[190:193], v[14:17]
	v_mfma_f32_16x16x32_bf16 v[10:13], v[142:145], v[190:193], v[10:13]
	s_setprio 0
	s_setprio 1
	v_mfma_f32_16x16x32_bf16 v[54:57], v[146:149], v[162:165], v[54:57]
	v_mfma_f32_16x16x32_bf16 v[50:53], v[154:157], v[162:165], v[50:53]
	v_mfma_f32_16x16x32_bf16 v[38:41], v[146:149], v[170:173], v[38:41]
	v_mfma_f32_16x16x32_bf16 v[34:37], v[154:157], v[170:173], v[34:37]
	v_mfma_f32_16x16x32_bf16 v[22:25], v[146:149], v[178:181], v[22:25]
	v_mfma_f32_16x16x32_bf16 v[18:21], v[154:157], v[178:181], v[18:21]
	v_mfma_f32_16x16x32_bf16 v[6:9], v[146:149], v[186:189], v[6:9]
	v_mfma_f32_16x16x32_bf16 v[2:5], v[154:157], v[186:189], v[2:5]
	v_mfma_f32_16x16x32_bf16 v[54:57], v[150:153], v[166:169], v[54:57]
	v_mfma_f32_16x16x32_bf16 v[50:53], v[158:161], v[166:169], v[50:53]
	v_mfma_f32_16x16x32_bf16 v[38:41], v[150:153], v[174:177], v[38:41]
	v_mfma_f32_16x16x32_bf16 v[34:37], v[158:161], v[174:177], v[34:37]
	v_mfma_f32_16x16x32_bf16 v[22:25], v[150:153], v[182:185], v[22:25]
	v_mfma_f32_16x16x32_bf16 v[18:21], v[158:161], v[182:185], v[18:21]
	v_mfma_f32_16x16x32_bf16 v[6:9], v[150:153], v[190:193], v[6:9]
	v_mfma_f32_16x16x32_bf16 v[2:5], v[158:161], v[190:193], v[2:5]
	s_setprio 0
	s_barrier
	s_add_i32 s18, 0, 0x18000
	s_add_i32 s19, 0, 0x1c000
	v_add_u32_e32 v142, s18, v197
	v_add_u32_e32 v158, s19, v197
	ds_read_b128 v[130:133], v142
	ds_read_b128 v[134:137], v142 offset:1024
	ds_read_b128 v[138:141], v142 offset:2048
	ds_read_b128 v[142:145], v142 offset:3072
	ds_read_b128 v[146:149], v158
	ds_read_b128 v[150:153], v158 offset:1024
	ds_read_b128 v[154:157], v158 offset:2048
	ds_read_b128 v[158:161], v158 offset:3072
	s_add_u32 s8, s8, 0x40000
	s_addc_u32 s9, s9, 0
	s_mov_b32 m0, s82
	v_lshl_add_u64 v[224:225], s[8:9], 0, v[0:1]
	ds_read_b128 v[162:165], v204 offset:32768
	ds_read_b128 v[166:169], v204 offset:33792
	ds_read_b128 v[170:173], v204 offset:34816
	ds_read_b128 v[174:177], v204 offset:35840
	ds_read_b128 v[178:181], v204 offset:36864
	ds_read_b128 v[182:185], v204 offset:37888
	ds_read_b128 v[186:189], v204 offset:38912
	ds_read_b128 v[190:193], v204 offset:39936
	global_load_lds_dwordx4 v[224:225], off
	v_lshl_add_u64 v[224:225], s[8:9], 0, v[208:209]
	s_mov_b32 m0, s83
	s_nop 0
	global_load_lds_dwordx4 v[224:225], off
	s_waitcnt vmcnt(8)
	s_waitcnt lgkmcnt(0)
	s_barrier
	s_setprio 1
	s_waitcnt lgkmcnt(0)
	v_mfma_f32_16x16x32_bf16 v[126:129], v[130:133], v[162:165], v[126:129]
	v_mfma_f32_16x16x32_bf16 v[122:125], v[138:141], v[162:165], v[122:125]
	v_mfma_f32_16x16x32_bf16 v[110:113], v[130:133], v[170:173], v[110:113]
	v_mfma_f32_16x16x32_bf16 v[106:109], v[138:141], v[170:173], v[106:109]
	v_mfma_f32_16x16x32_bf16 v[94:97], v[130:133], v[178:181], v[94:97]
	v_mfma_f32_16x16x32_bf16 v[90:93], v[138:141], v[178:181], v[90:93]
	v_mfma_f32_16x16x32_bf16 v[78:81], v[130:133], v[186:189], v[78:81]
	v_mfma_f32_16x16x32_bf16 v[74:77], v[138:141], v[186:189], v[74:77]
	v_mfma_f32_16x16x32_bf16 v[126:129], v[134:137], v[166:169], v[126:129]
	v_mfma_f32_16x16x32_bf16 v[122:125], v[142:145], v[166:169], v[122:125]
	v_mfma_f32_16x16x32_bf16 v[110:113], v[134:137], v[174:177], v[110:113]
	v_mfma_f32_16x16x32_bf16 v[106:109], v[142:145], v[174:177], v[106:109]
	v_mfma_f32_16x16x32_bf16 v[94:97], v[134:137], v[182:185], v[94:97]
	v_mfma_f32_16x16x32_bf16 v[90:93], v[142:145], v[182:185], v[90:93]
	v_mfma_f32_16x16x32_bf16 v[78:81], v[134:137], v[190:193], v[78:81]
	v_mfma_f32_16x16x32_bf16 v[74:77], v[142:145], v[190:193], v[74:77]
	s_setprio 0
	s_setprio 1
	v_mfma_f32_16x16x32_bf16 v[118:121], v[146:149], v[162:165], v[118:121]
	v_mfma_f32_16x16x32_bf16 v[114:117], v[154:157], v[162:165], v[114:117]
	v_mfma_f32_16x16x32_bf16 v[102:105], v[146:149], v[170:173], v[102:105]
	v_mfma_f32_16x16x32_bf16 v[98:101], v[154:157], v[170:173], v[98:101]
	v_mfma_f32_16x16x32_bf16 v[86:89], v[146:149], v[178:181], v[86:89]
	v_mfma_f32_16x16x32_bf16 v[82:85], v[154:157], v[178:181], v[82:85]
	v_mfma_f32_16x16x32_bf16 v[70:73], v[146:149], v[186:189], v[70:73]
	v_mfma_f32_16x16x32_bf16 v[66:69], v[154:157], v[186:189], v[66:69]
	v_mfma_f32_16x16x32_bf16 v[118:121], v[150:153], v[166:169], v[118:121]
	v_mfma_f32_16x16x32_bf16 v[114:117], v[158:161], v[166:169], v[114:117]
	v_mfma_f32_16x16x32_bf16 v[102:105], v[150:153], v[174:177], v[102:105]
	v_mfma_f32_16x16x32_bf16 v[98:101], v[158:161], v[174:177], v[98:101]
	v_mfma_f32_16x16x32_bf16 v[86:89], v[150:153], v[182:185], v[86:89]
	v_mfma_f32_16x16x32_bf16 v[82:85], v[158:161], v[182:185], v[82:85]
	v_mfma_f32_16x16x32_bf16 v[70:73], v[150:153], v[190:193], v[70:73]
	v_mfma_f32_16x16x32_bf16 v[66:69], v[158:161], v[190:193], v[66:69]
	s_setprio 0
	s_barrier
; #define PG8_STAGE(bufoff, gbase, voff) do { _Pragma("unroll") for (int _i = 0; _i < 2; ++_i) \
;         __builtin_amdgcn_global_load_lds((const unsigned*)((const char*)(gbase) + (voff)[_i]), (LAS unsigned*)(lds + (bufoff) + ldsw + _i * 8192), 16, 0, 0); } while (0)
; #define PG8_STAGE_A(bufoff, gbase, spf) do { _Pragma("unroll") for (int _i = 0; _i < 2; ++_i) \
;         __builtin_amdgcn_global_load_lds((const unsigned*)((const char*)(gbase) + (Epi::SPECIAL_ROWS && (spf) ? voffS[_i] : voffA[_i])), (LAS unsigned*)(lds + (bufoff) + ldsw + _i * 8192), 16, 0, 0); } while (0)
; #define PG8_LDA(dst, b, h) do { _Pragma("unroll") for (int m = 0; m < 4; ++m) _Pragma("unroll") for (int k = 0; k < 2; ++k) dst[m][k] = *(const LAS bf16x8*)(lds + PG8_SA(b, h) + aoff + m * 2048 + k * 1024); } while (0)
; #define PG8_MMA(ai, bj, At, Bt) do { __builtin_amdgcn_s_setprio(1); _Pragma("unroll") for (int m = 0; m < 4; ++m) _Pragma("unroll") for (int n = 0; n < 2; ++n) _Pragma("unroll") for (int k = 0; k < 2; ++k) \
;         acc[ai][bj][m][n] = __builtin_amdgcn_mfma_f32_16x16x32_bf16(Bt[n][k], At[m][k], acc[ai][bj][m][n], 0, 0, 0); __builtin_amdgcn_s_setprio(0); } while (0)
; #define PG8_WAIT_V(n) asm volatile("s_waitcnt vmcnt(" #n ")" ::: "memory")
; #define PG8_WAIT_L(n) asm volatile("s_waitcnt lgkmcnt(" #n ")" ::: "memory")
; #define PG8_BAR __builtin_amdgcn_s_barrier()
; #define PG8_SCHED __builtin_amdgcn_sched_barrier(0)
; template <class Epi>
; __device__ __forceinline__ void gemm_phase(LAS unsigned char* lds, const Gemm g, const Sched& S, const Epi& E) {
;     ...
;             PG8_LDA(At, 1, 1); PG8_STAGE(PG8_SB(1, 0), b3, voffB); PG8_STAGE(PG8_SB(1, 1), b3 + hstepB, voffB); PG8_STAGE_A(PG8_SA(1, 0), a3, sp2);
;             PG8_WAIT_V(8); PG8_WAIT_L(0); PG8_BAR; PG8_MMA(1, 0, At, B0); PG8_MMA(1, 1, At, B1); PG8_BAR; PG8_SCHED;
;         }
;         if (wr == 0) PG8_BAR;
	s_add_i32 s8, s18, s36
	v_lshl_add_u64 v[216:217], v[216:217], 0, s[20:21]
	s_mov_b32 m0, s8
	ds_read_b128 v[162:165], v204 offset:49152
	ds_read_b128 v[166:169], v204 offset:50176
	ds_read_b128 v[170:173], v204 offset:51200
	ds_read_b128 v[174:177], v204 offset:52224
	ds_read_b128 v[178:181], v204 offset:53248
	ds_read_b128 v[182:185], v204 offset:54272
	ds_read_b128 v[186:189], v204 offset:55296
	ds_read_b128 v[190:193], v204 offset:56320
	global_load_lds_dwordx4 v[216:217], off
	s_add_i32 m0, s8, 0x2000
	s_add_u32 s8, s22, 0x40080
	v_lshl_add_u64 v[216:217], v[218:219], 0, s[20:21]
	s_addc_u32 s9, s23, 0
	s_add_i32 s18, s19, s36
	global_load_lds_dwordx4 v[216:217], off
	v_lshl_add_u64 v[216:217], s[8:9], 0, v[0:1]
	s_mov_b32 m0, s18
	s_nop 0
	global_load_lds_dwordx4 v[216:217], off
	v_lshl_add_u64 v[216:217], s[8:9], 0, v[208:209]
	s_add_i32 m0, s18, 0x2000
	s_nop 0
	global_load_lds_dwordx4 v[216:217], off
	v_lshl_add_u64 v[216:217], v[220:221], 0, s[20:21]
	s_mov_b32 m0, s85
	s_nop 0
	global_load_lds_dwordx4 v[216:217], off
	v_lshl_add_u64 v[216:217], v[222:223], 0, s[20:21]
	s_mov_b32 m0, s86
	s_nop 0
	global_load_lds_dwordx4 v[216:217], off
	s_waitcnt vmcnt(8)
	s_waitcnt lgkmcnt(0)
	s_barrier
	s_setprio 1
	s_waitcnt lgkmcnt(0)
	v_mfma_f32_16x16x32_bf16 v[62:65], v[130:133], v[162:165], v[62:65]
	v_mfma_f32_16x16x32_bf16 v[58:61], v[138:141], v[162:165], v[58:61]
	v_mfma_f32_16x16x32_bf16 v[46:49], v[130:133], v[170:173], v[46:49]
	v_mfma_f32_16x16x32_bf16 v[42:45], v[138:141], v[170:173], v[42:45]
	v_mfma_f32_16x16x32_bf16 v[30:33], v[130:133], v[178:181], v[30:33]
	v_mfma_f32_16x16x32_bf16 v[26:29], v[138:141], v[178:181], v[26:29]
	v_mfma_f32_16x16x32_bf16 v[14:17], v[130:133], v[186:189], v[14:17]
	v_mfma_f32_16x16x32_bf16 v[10:13], v[138:141], v[186:189], v[10:13]
	v_mfma_f32_16x16x32_bf16 v[62:65], v[134:137], v[166:169], v[62:65]
	v_mfma_f32_16x16x32_bf16 v[58:61], v[142:145], v[166:169], v[58:61]
	v_mfma_f32_16x16x32_bf16 v[46:49], v[134:137], v[174:177], v[46:49]
	v_mfma_f32_16x16x32_bf16 v[42:45], v[142:145], v[174:177], v[42:45]
	v_mfma_f32_16x16x32_bf16 v[30:33], v[134:137], v[182:185], v[30:33]
	v_mfma_f32_16x16x32_bf16 v[26:29], v[142:145], v[182:185], v[26:29]
	v_mfma_f32_16x16x32_bf16 v[14:17], v[134:137], v[190:193], v[14:17]
	v_mfma_f32_16x16x32_bf16 v[10:13], v[142:145], v[190:193], v[10:13]
	s_setprio 0
	s_setprio 1
	v_mfma_f32_16x16x32_bf16 v[54:57], v[146:149], v[162:165], v[54:57]
	v_mfma_f32_16x16x32_bf16 v[50:53], v[154:157], v[162:165], v[50:53]
	v_mfma_f32_16x16x32_bf16 v[38:41], v[146:149], v[170:173], v[38:41]
	v_mfma_f32_16x16x32_bf16 v[34:37], v[154:157], v[170:173], v[34:37]
	v_mfma_f32_16x16x32_bf16 v[22:25], v[146:149], v[178:181], v[22:25]
	v_mfma_f32_16x16x32_bf16 v[18:21], v[154:157], v[178:181], v[18:21]
	v_mfma_f32_16x16x32_bf16 v[6:9], v[146:149], v[186:189], v[6:9]
	v_mfma_f32_16x16x32_bf16 v[2:5], v[154:157], v[186:189], v[2:5]
	v_mfma_f32_16x16x32_bf16 v[54:57], v[150:153], v[166:169], v[54:57]
	v_mfma_f32_16x16x32_bf16 v[50:53], v[158:161], v[166:169], v[50:53]
	v_mfma_f32_16x16x32_bf16 v[38:41], v[150:153], v[174:177], v[38:41]
	v_mfma_f32_16x16x32_bf16 v[34:37], v[158:161], v[174:177], v[34:37]
	v_mfma_f32_16x16x32_bf16 v[22:25], v[150:153], v[182:185], v[22:25]
	v_mfma_f32_16x16x32_bf16 v[18:21], v[158:161], v[182:185], v[18:21]
	v_mfma_f32_16x16x32_bf16 v[6:9], v[150:153], v[190:193], v[6:9]
	v_mfma_f32_16x16x32_bf16 v[2:5], v[158:161], v[190:193], v[2:5]
	s_setprio 0
	s_barrier
	s_add_i32 s46, s46, 2
	s_add_u32 s72, s72, 0x100
	s_addc_u32 s73, s73, 0
	s_add_u32 s30, s30, 0x100
	s_addc_u32 s31, s31, 0
	s_cmp_gt_u32 s46, 13
	s_cbranch_scc0 .LBB0_199
	s_and_b64 vcc, exec, s[16:17]
	s_cbranch_vccz .LBB0_202
	s_barrier

; #define PG8_STAGE(bufoff, gbase, voff) do { _Pragma("unroll") for (int _i = 0; _i < 2; ++_i) \
;         __builtin_amdgcn_global_load_lds((const unsigned*)((const char*)(gbase) + (voff)[_i]), (LAS unsigned*)(lds + (bufoff) + ldsw + _i * 8192), 16, 0, 0); } while (0)
; #define PG8_STAGE_A(bufoff, gbase, spf) do { _Pragma("unroll") for (int _i = 0; _i < 2; ++_i) \
;         __builtin_amdgcn_global_load_lds((const unsigned*)((const char*)(gbase) + (Epi::SPECIAL_ROWS && (spf) ? voffS[_i] : voffA[_i])), (LAS unsigned*)(lds + (bufoff) + ldsw + _i * 8192), 16, 0, 0); } while (0)
; #define PG8_LDA(dst, b, h) do { _Pragma("unroll") for (int m = 0; m < 4; ++m) _Pragma("unroll") for (int k = 0; k < 2; ++k) dst[m][k] = *(const LAS bf16x8*)(lds + PG8_SA(b, h) + aoff + m * 2048 + k * 1024); } while (0)
; #define PG8_LDB(dst, b, h) do { _Pragma("unroll") for (int n = 0; n < 2; ++n) _Pragma("unroll") for (int k = 0; k < 2; ++k) dst[n][k] = *(const LAS bf16x8*)(lds + PG8_SB(b, h) + boff + n * 2048 + k * 1024); } while (0)
; #define PG8_WAIT_V(n) asm volatile("s_waitcnt vmcnt(" #n ")" ::: "memory")
; #define PG8_WAIT_L(n) asm volatile("s_waitcnt lgkmcnt(" #n ")" ::: "memory")
; #define PG8_BAR __builtin_amdgcn_s_barrier()
; template <class Epi>
; __device__ __forceinline__ void gemm_phase(LAS unsigned char* lds, const Gemm g, const Sched& S, const Epi& E) {
;     ...
;         for (int t = 0; t < nt; t += 2) {
;             const bool last = (t == nt - 2);
;             const char* a1 = cA + (size_t)((t + 1) & kmask) * kstep;
;             const char* a2 = last ? nA : cA + (size_t)((t + 2) & kmask) * kstep; const char* b2 = last ? nB : cB + (size_t)((t + 2) & kmask) * kstep;
;             const char* a3 = a2 + kstep; const char* b3 = b2 + kstep;
;             const bool sp2 = last ? nsp : csp; const size_t hA2 = last ? nhA : chA;
;             PG8_LDB(B0, 0, 0); PG8_LDB(B1, 0, 1); PG8_SCHED; PG8_LDA(At, 0, 0); PG8_STAGE_A(PG8_SA(1, 1), a1 + chA, csp);
;             PG8_WAIT_V(8); PG8_WAIT_L(0); PG8_BAR; PG8_MMA(0, 0, At, B0); PG8_MMA(0, 1, At, B1); PG8_BAR; PG8_SCHED;
;             PG8_LDA(At, 0, 1); PG8_STAGE(PG8_SB(0, 0), b2, voffB); PG8_STAGE(PG8_SB(0, 1), b2 + hstepB, voffB); PG8_STAGE_A(PG8_SA(0, 0), a2, sp2);
;             PG8_WAIT_V(8); PG8_WAIT_L(0); PG8_BAR; PG8_MMA(1, 0, At, B0); PG8_MMA(1, 1, At, B1); PG8_BAR; PG8_SCHED;
.LBB0_332:
	s_add_u32 s8, s12, 0xfffc0080
	s_addc_u32 s9, s13, -1
	s_add_i32 s18, 0, 0x10000
	s_cmp_eq_u32 s81, 12
	s_cselect_b32 s9, s1, s9
	s_cselect_b32 s8, s35, s8
	v_add_u32_e32 v152, s18, v154
	s_cselect_b32 s23, s17, s31
	s_cselect_b32 s22, s80, s30
	s_add_i32 s54, 0, 0x14000
	ds_read_b128 v[140:143], v152
	ds_read_b128 v[144:147], v152 offset:1024
	ds_read_b128 v[148:151], v152 offset:2048
	ds_read_b128 v[156:159], v152 offset:3072
	v_add_u32_e32 v152, s54, v154
	ds_read_b128 v[160:163], v152
	ds_read_b128 v[164:167], v152 offset:1024
	ds_read_b128 v[168:171], v152 offset:2048
	ds_read_b128 v[172:175], v152 offset:3072
	v_lshl_add_u64 v[152:153], s[12:13], 0, v[136:137]
	s_add_i32 m0, s63, 0xc000
	ds_read_b128 v[176:179], v155
	ds_read_b128 v[180:183], v155 offset:1024
	ds_read_b128 v[184:187], v155 offset:2048
	ds_read_b128 v[188:191], v155 offset:3072
	ds_read_b128 v[208:211], v155 offset:4096
	ds_read_b128 v[212:215], v155 offset:5120
	ds_read_b128 v[216:219], v155 offset:6144
	ds_read_b128 v[220:223], v155 offset:7168
	global_load_lds_dwordx4 v[152:153], off
	v_lshl_add_u64 v[152:153], s[12:13], 0, v[138:139]
	s_add_i32 m0, s63, 0xe000
	s_nop 0
	global_load_lds_dwordx4 v[152:153], off
	s_cmp_eq_i32 s81, -2
	s_cbranch_scc1 .Lfi_skip6
	s_waitcnt vmcnt(8)
.Lfi_skip6:
	s_waitcnt lgkmcnt(0)
	s_barrier
	s_setprio 1
	s_waitcnt lgkmcnt(0)
	v_mfma_f32_16x16x32_bf16 v[126:129], v[140:143], v[176:179], v[126:129]
	v_mfma_f32_16x16x32_bf16 v[122:125], v[148:151], v[176:179], v[122:125]
	v_mfma_f32_16x16x32_bf16 v[110:113], v[140:143], v[184:187], v[110:113]
	v_mfma_f32_16x16x32_bf16 v[106:109], v[148:151], v[184:187], v[106:109]
	v_mfma_f32_16x16x32_bf16 v[94:97], v[140:143], v[208:211], v[94:97]
	v_mfma_f32_16x16x32_bf16 v[90:93], v[148:151], v[208:211], v[90:93]
	v_mfma_f32_16x16x32_bf16 v[78:81], v[140:143], v[216:219], v[78:81]
	v_mfma_f32_16x16x32_bf16 v[74:77], v[148:151], v[216:219], v[74:77]
	v_mfma_f32_16x16x32_bf16 v[126:129], v[144:147], v[180:183], v[126:129]
	v_mfma_f32_16x16x32_bf16 v[122:125], v[156:159], v[180:183], v[122:125]
	v_mfma_f32_16x16x32_bf16 v[110:113], v[144:147], v[188:191], v[110:113]
	v_mfma_f32_16x16x32_bf16 v[106:109], v[156:159], v[188:191], v[106:109]
	v_mfma_f32_16x16x32_bf16 v[94:97], v[144:147], v[212:215], v[94:97]
	v_mfma_f32_16x16x32_bf16 v[90:93], v[156:159], v[212:215], v[90:93]
	v_mfma_f32_16x16x32_bf16 v[78:81], v[144:147], v[220:223], v[78:81]
	v_mfma_f32_16x16x32_bf16 v[74:77], v[156:159], v[220:223], v[74:77]
	s_setprio 0
	s_setprio 1
	v_mfma_f32_16x16x32_bf16 v[118:121], v[160:163], v[176:179], v[118:121]
	v_mfma_f32_16x16x32_bf16 v[114:117], v[168:171], v[176:179], v[114:117]
	v_mfma_f32_16x16x32_bf16 v[102:105], v[160:163], v[184:187], v[102:105]
	v_mfma_f32_16x16x32_bf16 v[98:101], v[168:171], v[184:187], v[98:101]
	v_mfma_f32_16x16x32_bf16 v[86:89], v[160:163], v[208:211], v[86:89]
	v_mfma_f32_16x16x32_bf16 v[82:85], v[168:171], v[208:211], v[82:85]
	v_mfma_f32_16x16x32_bf16 v[70:73], v[160:163], v[216:219], v[70:73]
	v_mfma_f32_16x16x32_bf16 v[66:69], v[168:171], v[216:219], v[66:69]
	v_mfma_f32_16x16x32_bf16 v[118:121], v[164:167], v[180:183], v[118:121]
	v_mfma_f32_16x16x32_bf16 v[114:117], v[172:175], v[180:183], v[114:117]
	v_mfma_f32_16x16x32_bf16 v[102:105], v[164:167], v[188:191], v[102:105]
	v_mfma_f32_16x16x32_bf16 v[98:101], v[172:175], v[188:191], v[98:101]
	v_mfma_f32_16x16x32_bf16 v[86:89], v[164:167], v[212:215], v[86:89]
	v_mfma_f32_16x16x32_bf16 v[82:85], v[172:175], v[212:215], v[82:85]
	v_mfma_f32_16x16x32_bf16 v[70:73], v[164:167], v[220:223], v[70:73]
	v_mfma_f32_16x16x32_bf16 v[66:69], v[172:175], v[220:223], v[66:69]
	s_setprio 0
	s_barrier
	s_add_i32 s18, s18, s46
	v_lshl_add_u64 v[152:153], s[22:23], 0, v[132:133]
	s_mov_b32 m0, s18
	ds_read_b128 v[176:179], v155 offset:16384
	ds_read_b128 v[180:183], v155 offset:17408
	ds_read_b128 v[184:187], v155 offset:18432
	ds_read_b128 v[188:191], v155 offset:19456
	ds_read_b128 v[208:211], v155 offset:20480
	ds_read_b128 v[212:215], v155 offset:21504
	ds_read_b128 v[216:219], v155 offset:22528
	ds_read_b128 v[220:223], v155 offset:23552
	global_load_lds_dwordx4 v[152:153], off
	s_add_i32 m0, s18, 0x2000
	s_add_u32 s18, s22, 0x40000
	v_lshl_add_u64 v[192:193], s[22:23], 0, v[130:131]
	s_addc_u32 s19, s23, 0
	s_add_i32 s54, s54, s46
	global_load_lds_dwordx4 v[192:193], off
	v_lshl_add_u64 v[204:205], s[18:19], 0, v[132:133]
	s_mov_b32 m0, s54
	v_lshl_add_u64 v[224:225], s[8:9], 0, v[130:131]
	global_load_lds_dwordx4 v[204:205], off
	v_lshl_add_u64 v[204:205], s[18:19], 0, v[130:131]
	s_add_i32 m0, s54, 0x2000
	s_nop 0
	global_load_lds_dwordx4 v[204:205], off
	v_lshl_add_u64 v[204:205], s[8:9], 0, v[132:133]
	s_mov_b32 m0, s63
	s_nop 0
	global_load_lds_dwordx4 v[204:205], off
	s_mov_b32 m0, s64
	s_nop 0
	global_load_lds_dwordx4 v[224:225], off
	s_cmp_eq_i32 s81, -2
	s_cbranch_scc1 .Lfi_skip5
	s_waitcnt vmcnt(8)
; #define PG8_STAGE_A(bufoff, gbase, spf) do { _Pragma("unroll") for (int _i = 0; _i < 2; ++_i) \
;         __builtin_amdgcn_global_load_lds((const unsigned*)((const char*)(gbase) + (Epi::SPECIAL_ROWS && (spf) ? voffS[_i] : voffA[_i])), (LAS unsigned*)(lds + (bufoff) + ldsw + _i * 8192), 16, 0, 0); } while (0)
; #define PG8_LDA(dst, b, h) do { _Pragma("unroll") for (int m = 0; m < 4; ++m) _Pragma("unroll") for (int k = 0; k < 2; ++k) dst[m][k] = *(const LAS bf16x8*)(lds + PG8_SA(b, h) + aoff + m * 2048 + k * 1024); } while (0)
; #define PG8_LDB(dst, b, h) do { _Pragma("unroll") for (int n = 0; n < 2; ++n) _Pragma("unroll") for (int k = 0; k < 2; ++k) dst[n][k] = *(const LAS bf16x8*)(lds + PG8_SB(b, h) + boff + n * 2048 + k * 1024); } while (0)
; #define PG8_MMA(ai, bj, At, Bt) do { __builtin_amdgcn_s_setprio(1); _Pragma("unroll") for (int m = 0; m < 4; ++m) _Pragma("unroll") for (int n = 0; n < 2; ++n) _Pragma("unroll") for (int k = 0; k < 2; ++k) \
;         acc[ai][bj][m][n] = __builtin_amdgcn_mfma_f32_16x16x32_bf16(Bt[n][k], At[m][k], acc[ai][bj][m][n], 0, 0, 0); __builtin_amdgcn_s_setprio(0); } while (0)
; #define PG8_WAIT_V(n) asm volatile("s_waitcnt vmcnt(" #n ")" ::: "memory")
; #define PG8_WAIT_L(n) asm volatile("s_waitcnt lgkmcnt(" #n ")" ::: "memory")
; #define PG8_BAR __builtin_amdgcn_s_barrier()
; #define PG8_SCHED __builtin_amdgcn_sched_barrier(0)
; template <class Epi>
; __device__ __forceinline__ void gemm_phase(LAS unsigned char* lds, const Gemm g, const Sched& S, const Epi& E) {
;     ...
;             PG8_WAIT_V(8); PG8_WAIT_L(0); PG8_BAR; PG8_MMA(1, 0, At, B0); PG8_MMA(1, 1, At, B1); PG8_BAR; PG8_SCHED;
;             PG8_LDB(B0, 1, 0); PG8_LDB(B1, 1, 1); PG8_SCHED; PG8_LDA(At, 1, 0); PG8_STAGE_A(PG8_SA(0, 1), a2 + hA2, sp2);
;             PG8_WAIT_V(8); PG8_WAIT_L(0); PG8_BAR; PG8_MMA(0, 0, At, B0); PG8_MMA(0, 1, At, B1); PG8_BAR; PG8_SCHED;
.Lfi_skip5:
	s_waitcnt lgkmcnt(0)
	s_barrier
	s_setprio 1
	s_waitcnt lgkmcnt(0)
	v_mfma_f32_16x16x32_bf16 v[62:65], v[140:143], v[176:179], v[62:65]
	v_mfma_f32_16x16x32_bf16 v[58:61], v[148:151], v[176:179], v[58:61]
	v_mfma_f32_16x16x32_bf16 v[46:49], v[140:143], v[184:187], v[46:49]
	v_mfma_f32_16x16x32_bf16 v[42:45], v[148:151], v[184:187], v[42:45]
	v_mfma_f32_16x16x32_bf16 v[30:33], v[140:143], v[208:211], v[30:33]
	v_mfma_f32_16x16x32_bf16 v[26:29], v[148:151], v[208:211], v[26:29]
	v_mfma_f32_16x16x32_bf16 v[14:17], v[140:143], v[216:219], v[14:17]
	v_mfma_f32_16x16x32_bf16 v[10:13], v[148:151], v[216:219], v[10:13]
	v_mfma_f32_16x16x32_bf16 v[62:65], v[144:147], v[180:183], v[62:65]
	v_mfma_f32_16x16x32_bf16 v[58:61], v[156:159], v[180:183], v[58:61]
	v_mfma_f32_16x16x32_bf16 v[46:49], v[144:147], v[188:191], v[46:49]
	v_mfma_f32_16x16x32_bf16 v[42:45], v[156:159], v[188:191], v[42:45]
	v_mfma_f32_16x16x32_bf16 v[30:33], v[144:147], v[212:215], v[30:33]
	v_mfma_f32_16x16x32_bf16 v[26:29], v[156:159], v[212:215], v[26:29]
	v_mfma_f32_16x16x32_bf16 v[14:17], v[144:147], v[220:223], v[14:17]
	v_mfma_f32_16x16x32_bf16 v[10:13], v[156:159], v[220:223], v[10:13]
	s_setprio 0
	s_setprio 1
	v_mfma_f32_16x16x32_bf16 v[54:57], v[160:163], v[176:179], v[54:57]
	v_mfma_f32_16x16x32_bf16 v[50:53], v[168:171], v[176:179], v[50:53]
	v_mfma_f32_16x16x32_bf16 v[38:41], v[160:163], v[184:187], v[38:41]
	v_mfma_f32_16x16x32_bf16 v[34:37], v[168:171], v[184:187], v[34:37]
	v_mfma_f32_16x16x32_bf16 v[22:25], v[160:163], v[208:211], v[22:25]
	v_mfma_f32_16x16x32_bf16 v[18:21], v[168:171], v[208:211], v[18:21]
	v_mfma_f32_16x16x32_bf16 v[6:9], v[160:163], v[216:219], v[6:9]
	v_mfma_f32_16x16x32_bf16 v[2:5], v[168:171], v[216:219], v[2:5]
	v_mfma_f32_16x16x32_bf16 v[54:57], v[164:167], v[180:183], v[54:57]
	v_mfma_f32_16x16x32_bf16 v[50:53], v[172:175], v[180:183], v[50:53]
	v_mfma_f32_16x16x32_bf16 v[38:41], v[164:167], v[188:191], v[38:41]
	v_mfma_f32_16x16x32_bf16 v[34:37], v[172:175], v[188:191], v[34:37]
	v_mfma_f32_16x16x32_bf16 v[22:25], v[164:167], v[212:215], v[22:25]
	v_mfma_f32_16x16x32_bf16 v[18:21], v[172:175], v[212:215], v[18:21]
	v_mfma_f32_16x16x32_bf16 v[6:9], v[164:167], v[220:223], v[6:9]
	v_mfma_f32_16x16x32_bf16 v[2:5], v[172:175], v[220:223], v[2:5]
	s_setprio 0
	s_barrier
	s_add_i32 s18, 0, 0x18000
	s_add_i32 s19, 0, 0x1c000
	v_add_u32_e32 v156, s18, v154
	v_add_u32_e32 v172, s19, v154
	ds_read_b128 v[140:143], v156
	ds_read_b128 v[144:147], v156 offset:1024
	ds_read_b128 v[148:151], v156 offset:2048
	ds_read_b128 v[156:159], v156 offset:3072
	ds_read_b128 v[160:163], v172
	ds_read_b128 v[164:167], v172 offset:1024
	ds_read_b128 v[168:171], v172 offset:2048
	ds_read_b128 v[172:175], v172 offset:3072
	s_add_u32 s8, s8, 0x40000
	s_addc_u32 s9, s9, 0
	s_mov_b32 m0, s65
	v_lshl_add_u64 v[226:227], s[8:9], 0, v[132:133]
	ds_read_b128 v[176:179], v155 offset:32768
	ds_read_b128 v[180:183], v155 offset:33792
	ds_read_b128 v[184:187], v155 offset:34816
	ds_read_b128 v[188:191], v155 offset:35840
	ds_read_b128 v[208:211], v155 offset:36864
	ds_read_b128 v[212:215], v155 offset:37888
	ds_read_b128 v[216:219], v155 offset:38912
	ds_read_b128 v[220:223], v155 offset:39936
	global_load_lds_dwordx4 v[226:227], off
	v_lshl_add_u64 v[226:227], s[8:9], 0, v[130:131]
	s_mov_b32 m0, s72
	s_nop 0
	global_load_lds_dwordx4 v[226:227], off
	s_waitcnt vmcnt(8)
	s_waitcnt lgkmcnt(0)
	s_barrier
	s_setprio 1
	s_waitcnt lgkmcnt(0)
	v_mfma_f32_16x16x32_bf16 v[126:129], v[140:143], v[176:179], v[126:129]
	v_mfma_f32_16x16x32_bf16 v[122:125], v[148:151], v[176:179], v[122:125]
	v_mfma_f32_16x16x32_bf16 v[110:113], v[140:143], v[184:187], v[110:113]
	v_mfma_f32_16x16x32_bf16 v[106:109], v[148:151], v[184:187], v[106:109]
	v_mfma_f32_16x16x32_bf16 v[94:97], v[140:143], v[208:211], v[94:97]
	v_mfma_f32_16x16x32_bf16 v[90:93], v[148:151], v[208:211], v[90:93]
	v_mfma_f32_16x16x32_bf16 v[78:81], v[140:143], v[216:219], v[78:81]
	v_mfma_f32_16x16x32_bf16 v[74:77], v[148:151], v[216:219], v[74:77]
	v_mfma_f32_16x16x32_bf16 v[126:129], v[144:147], v[180:183], v[126:129]
	v_mfma_f32_16x16x32_bf16 v[122:125], v[156:159], v[180:183], v[122:125]
	v_mfma_f32_16x16x32_bf16 v[110:113], v[144:147], v[188:191], v[110:113]
	v_mfma_f32_16x16x32_bf16 v[106:109], v[156:159], v[188:191], v[106:109]
	v_mfma_f32_16x16x32_bf16 v[94:97], v[144:147], v[212:215], v[94:97]
	v_mfma_f32_16x16x32_bf16 v[90:93], v[156:159], v[212:215], v[90:93]
	v_mfma_f32_16x16x32_bf16 v[78:81], v[144:147], v[220:223], v[78:81]
	v_mfma_f32_16x16x32_bf16 v[74:77], v[156:159], v[220:223], v[74:77]
	s_setprio 0
	s_setprio 1
	v_mfma_f32_16x16x32_bf16 v[118:121], v[160:163], v[176:179], v[118:121]
	v_mfma_f32_16x16x32_bf16 v[114:117], v[168:171], v[176:179], v[114:117]
	v_mfma_f32_16x16x32_bf16 v[102:105], v[160:163], v[184:187], v[102:105]
	v_mfma_f32_16x16x32_bf16 v[98:101], v[168:171], v[184:187], v[98:101]
	v_mfma_f32_16x16x32_bf16 v[86:89], v[160:163], v[208:211], v[86:89]
	v_mfma_f32_16x16x32_bf16 v[82:85], v[168:171], v[208:211], v[82:85]
	v_mfma_f32_16x16x32_bf16 v[70:73], v[160:163], v[216:219], v[70:73]
	v_mfma_f32_16x16x32_bf16 v[66:69], v[168:171], v[216:219], v[66:69]
	v_mfma_f32_16x16x32_bf16 v[118:121], v[164:167], v[180:183], v[118:121]
	v_mfma_f32_16x16x32_bf16 v[114:117], v[172:175], v[180:183], v[114:117]
	v_mfma_f32_16x16x32_bf16 v[102:105], v[164:167], v[188:191], v[102:105]
	v_mfma_f32_16x16x32_bf16 v[98:101], v[172:175], v[188:191], v[98:101]
	v_mfma_f32_16x16x32_bf16 v[86:89], v[164:167], v[212:215], v[86:89]
	v_mfma_f32_16x16x32_bf16 v[82:85], v[172:175], v[212:215], v[82:85]
	v_mfma_f32_16x16x32_bf16 v[70:73], v[164:167], v[220:223], v[70:73]
	v_mfma_f32_16x16x32_bf16 v[66:69], v[172:175], v[220:223], v[66:69]
	s_setprio 0
	s_barrier
; #define PG8_STAGE(bufoff, gbase, voff) do { _Pragma("unroll") for (int _i = 0; _i < 2; ++_i) \
;         __builtin_amdgcn_global_load_lds((const unsigned*)((const char*)(gbase) + (voff)[_i]), (LAS unsigned*)(lds + (bufoff) + ldsw + _i * 8192), 16, 0, 0); } while (0)
; #define PG8_STAGE_A(bufoff, gbase, spf) do { _Pragma("unroll") for (int _i = 0; _i < 2; ++_i) \
;         __builtin_amdgcn_global_load_lds((const unsigned*)((const char*)(gbase) + (Epi::SPECIAL_ROWS && (spf) ? voffS[_i] : voffA[_i])), (LAS unsigned*)(lds + (bufoff) + ldsw + _i * 8192), 16, 0, 0); } while (0)
; #define PG8_LDA(dst, b, h) do { _Pragma("unroll") for (int m = 0; m < 4; ++m) _Pragma("unroll") for (int k = 0; k < 2; ++k) dst[m][k] = *(const LAS bf16x8*)(lds + PG8_SA(b, h) + aoff + m * 2048 + k * 1024); } while (0)
; #define PG8_MMA(ai, bj, At, Bt) do { __builtin_amdgcn_s_setprio(1); _Pragma("unroll") for (int m = 0; m < 4; ++m) _Pragma("unroll") for (int n = 0; n < 2; ++n) _Pragma("unroll") for (int k = 0; k < 2; ++k) \
;         acc[ai][bj][m][n] = __builtin_amdgcn_mfma_f32_16x16x32_bf16(Bt[n][k], At[m][k], acc[ai][bj][m][n], 0, 0, 0); __builtin_amdgcn_s_setprio(0); } while (0)
; #define PG8_WAIT_V(n) asm volatile("s_waitcnt vmcnt(" #n ")" ::: "memory")
; #define PG8_WAIT_L(n) asm volatile("s_waitcnt lgkmcnt(" #n ")" ::: "memory")
; #define PG8_BAR __builtin_amdgcn_s_barrier()
; #define PG8_SCHED __builtin_amdgcn_sched_barrier(0)
; template <class Epi>
; __device__ __forceinline__ void gemm_phase(LAS unsigned char* lds, const Gemm g, const Sched& S, const Epi& E) {
;     ...
;             PG8_LDA(At, 1, 1); PG8_STAGE(PG8_SB(1, 0), b3, voffB); PG8_STAGE(PG8_SB(1, 1), b3 + hstepB, voffB); PG8_STAGE_A(PG8_SA(1, 0), a3, sp2);
;             PG8_WAIT_V(8); PG8_WAIT_L(0); PG8_BAR; PG8_MMA(1, 0, At, B0); PG8_MMA(1, 1, At, B1); PG8_BAR; PG8_SCHED;
;         }
;         if (wr == 0) PG8_BAR;
	s_add_i32 s8, s18, s46
	v_lshl_add_u64 v[152:153], v[152:153], 0, s[20:21]
	s_mov_b32 m0, s8
	ds_read_b128 v[176:179], v155 offset:49152
	ds_read_b128 v[180:183], v155 offset:50176
	ds_read_b128 v[184:187], v155 offset:51200
	ds_read_b128 v[188:191], v155 offset:52224
	ds_read_b128 v[208:211], v155 offset:53248
	ds_read_b128 v[212:215], v155 offset:54272
	ds_read_b128 v[216:219], v155 offset:55296
	ds_read_b128 v[220:223], v155 offset:56320
	global_load_lds_dwordx4 v[152:153], off
	s_add_i32 m0, s8, 0x2000
	s_add_u32 s8, s22, 0x40080
	v_lshl_add_u64 v[152:153], v[192:193], 0, s[20:21]
	s_addc_u32 s9, s23, 0
	s_add_i32 s18, s19, s46
	global_load_lds_dwordx4 v[152:153], off
	v_lshl_add_u64 v[152:153], s[8:9], 0, v[132:133]
	s_mov_b32 m0, s18
	s_nop 0
	global_load_lds_dwordx4 v[152:153], off
	v_lshl_add_u64 v[152:153], s[8:9], 0, v[130:131]
	s_add_i32 m0, s18, 0x2000
	s_nop 0
	global_load_lds_dwordx4 v[152:153], off
	v_lshl_add_u64 v[152:153], v[204:205], 0, s[20:21]
	s_mov_b32 m0, s73
	s_nop 0
	global_load_lds_dwordx4 v[152:153], off
	v_lshl_add_u64 v[152:153], v[224:225], 0, s[20:21]
	s_mov_b32 m0, s74
	s_nop 0
	global_load_lds_dwordx4 v[152:153], off
	s_waitcnt vmcnt(8)
	s_waitcnt lgkmcnt(0)
	s_barrier
	s_setprio 1
	s_waitcnt lgkmcnt(0)
	v_mfma_f32_16x16x32_bf16 v[62:65], v[140:143], v[176:179], v[62:65]
	v_mfma_f32_16x16x32_bf16 v[58:61], v[148:151], v[176:179], v[58:61]
	v_mfma_f32_16x16x32_bf16 v[46:49], v[140:143], v[184:187], v[46:49]
	v_mfma_f32_16x16x32_bf16 v[42:45], v[148:151], v[184:187], v[42:45]
	v_mfma_f32_16x16x32_bf16 v[30:33], v[140:143], v[208:211], v[30:33]
	v_mfma_f32_16x16x32_bf16 v[26:29], v[148:151], v[208:211], v[26:29]
	v_mfma_f32_16x16x32_bf16 v[14:17], v[140:143], v[216:219], v[14:17]
	v_mfma_f32_16x16x32_bf16 v[10:13], v[148:151], v[216:219], v[10:13]
	v_mfma_f32_16x16x32_bf16 v[62:65], v[144:147], v[180:183], v[62:65]
	v_mfma_f32_16x16x32_bf16 v[58:61], v[156:159], v[180:183], v[58:61]
	v_mfma_f32_16x16x32_bf16 v[46:49], v[144:147], v[188:191], v[46:49]
	v_mfma_f32_16x16x32_bf16 v[42:45], v[156:159], v[188:191], v[42:45]
	v_mfma_f32_16x16x32_bf16 v[30:33], v[144:147], v[212:215], v[30:33]
	v_mfma_f32_16x16x32_bf16 v[26:29], v[156:159], v[212:215], v[26:29]
	v_mfma_f32_16x16x32_bf16 v[14:17], v[144:147], v[220:223], v[14:17]
	v_mfma_f32_16x16x32_bf16 v[10:13], v[156:159], v[220:223], v[10:13]
	s_setprio 0
	s_setprio 1
	v_mfma_f32_16x16x32_bf16 v[54:57], v[160:163], v[176:179], v[54:57]
	v_mfma_f32_16x16x32_bf16 v[50:53], v[168:171], v[176:179], v[50:53]
	v_mfma_f32_16x16x32_bf16 v[38:41], v[160:163], v[184:187], v[38:41]
	v_mfma_f32_16x16x32_bf16 v[34:37], v[168:171], v[184:187], v[34:37]
	v_mfma_f32_16x16x32_bf16 v[22:25], v[160:163], v[208:211], v[22:25]
	v_mfma_f32_16x16x32_bf16 v[18:21], v[168:171], v[208:211], v[18:21]
	v_mfma_f32_16x16x32_bf16 v[6:9], v[160:163], v[216:219], v[6:9]
	v_mfma_f32_16x16x32_bf16 v[2:5], v[168:171], v[216:219], v[2:5]
	v_mfma_f32_16x16x32_bf16 v[54:57], v[164:167], v[180:183], v[54:57]
	v_mfma_f32_16x16x32_bf16 v[50:53], v[172:175], v[180:183], v[50:53]
	v_mfma_f32_16x16x32_bf16 v[38:41], v[164:167], v[188:191], v[38:41]
	v_mfma_f32_16x16x32_bf16 v[34:37], v[172:175], v[188:191], v[34:37]
	v_mfma_f32_16x16x32_bf16 v[22:25], v[164:167], v[212:215], v[22:25]
	v_mfma_f32_16x16x32_bf16 v[18:21], v[172:175], v[212:215], v[18:21]
	v_mfma_f32_16x16x32_bf16 v[6:9], v[164:167], v[220:223], v[6:9]
	v_mfma_f32_16x16x32_bf16 v[2:5], v[172:175], v[220:223], v[2:5]
	s_setprio 0
	s_barrier
	s_add_i32 s81, s81, 2
	s_add_u32 s12, s12, 0x100
	s_addc_u32 s13, s13, 0
	s_add_u32 s30, s30, 0x100
	s_addc_u32 s31, s31, 0
	s_cmp_gt_u32 s81, 13
	s_cbranch_scc0 .LBB0_332
	s_and_b64 vcc, exec, s[14:15]
	s_cbranch_vccz .LBB0_335
	s_barrier

; #define PG8_STAGE(bufoff, gbase, voff) do { _Pragma("unroll") for (int _i = 0; _i < 2; ++_i) \
;         __builtin_amdgcn_global_load_lds((const unsigned*)((const char*)(gbase) + (voff)[_i]), (LAS unsigned*)(lds + (bufoff) + ldsw + _i * 8192), 16, 0, 0); } while (0)
; #define PG8_STAGE_A(bufoff, gbase, spf) do { _Pragma("unroll") for (int _i = 0; _i < 2; ++_i) \
;         __builtin_amdgcn_global_load_lds((const unsigned*)((const char*)(gbase) + (Epi::SPECIAL_ROWS && (spf) ? voffS[_i] : voffA[_i])), (LAS unsigned*)(lds + (bufoff) + ldsw + _i * 8192), 16, 0, 0); } while (0)
; #define PG8_LDA(dst, b, h) do { _Pragma("unroll") for (int m = 0; m < 4; ++m) _Pragma("unroll") for (int k = 0; k < 2; ++k) dst[m][k] = *(const LAS bf16x8*)(lds + PG8_SA(b, h) + aoff + m * 2048 + k * 1024); } while (0)
; #define PG8_LDB(dst, b, h) do { _Pragma("unroll") for (int n = 0; n < 2; ++n) _Pragma("unroll") for (int k = 0; k < 2; ++k) dst[n][k] = *(const LAS bf16x8*)(lds + PG8_SB(b, h) + boff + n * 2048 + k * 1024); } while (0)
; #define PG8_WAIT_V(n) asm volatile("s_waitcnt vmcnt(" #n ")" ::: "memory")
; #define PG8_WAIT_L(n) asm volatile("s_waitcnt lgkmcnt(" #n ")" ::: "memory")
; #define PG8_BAR __builtin_amdgcn_s_barrier()
; template <class Epi>
; __device__ __forceinline__ void gemm_phase(LAS unsigned char* lds, const Gemm g, const Sched& S, const Epi& E) {
;     ...
;         for (int t = 0; t < nt; t += 2) {
;             const bool last = (t == nt - 2);
;             const char* a1 = cA + (size_t)((t + 1) & kmask) * kstep;
;             const char* a2 = last ? nA : cA + (size_t)((t + 2) & kmask) * kstep; const char* b2 = last ? nB : cB + (size_t)((t + 2) & kmask) * kstep;
;             const char* a3 = a2 + kstep; const char* b3 = b2 + kstep;
;             const bool sp2 = last ? nsp : csp; const size_t hA2 = last ? nhA : chA;
;             PG8_LDB(B0, 0, 0); PG8_LDB(B1, 0, 1); PG8_SCHED; PG8_LDA(At, 0, 0); PG8_STAGE_A(PG8_SA(1, 1), a1 + chA, csp);
;             PG8_WAIT_V(8); PG8_WAIT_L(0); PG8_BAR; PG8_MMA(0, 0, At, B0); PG8_MMA(0, 1, At, B1); PG8_BAR; PG8_SCHED;
;             PG8_LDA(At, 0, 1); PG8_STAGE(PG8_SB(0, 0), b2, voffB); PG8_STAGE(PG8_SB(0, 1), b2 + hstepB, voffB); PG8_STAGE_A(PG8_SA(0, 0), a2, sp2);
;             PG8_WAIT_V(8); PG8_WAIT_L(0); PG8_BAR; PG8_MMA(1, 0, At, B0); PG8_MMA(1, 1, At, B1); PG8_BAR; PG8_SCHED;
.LBB0_637:
	s_add_u32 s8, s12, 0xfffc0080
	s_addc_u32 s9, s13, -1
	s_add_i32 s34, 0, 0x10000
	s_cmp_eq_u32 s44, 12
	s_cselect_b32 s9, s1, s9
	s_cselect_b32 s8, s2, s8
	v_add_u32_e32 v0, s34, v135
	s_cselect_b32 s17, s22, s43
	s_cselect_b32 s16, s23, s42
	s_add_i32 s45, 0, 0x14000
	ds_read_b128 v[156:159], v0
	ds_read_b128 v[160:163], v0 offset:1024
	ds_read_b128 v[164:167], v0 offset:2048
	ds_read_b128 v[168:171], v0 offset:3072
	v_add_u32_e32 v0, s45, v135
	ds_read_b128 v[172:175], v0
	ds_read_b128 v[176:179], v0 offset:1024
	ds_read_b128 v[180:183], v0 offset:2048
	ds_read_b128 v[184:187], v0 offset:3072
	v_lshl_add_u64 v[192:193], s[12:13], 0, v[152:153]
	s_add_i32 m0, s19, 0xc000
	ds_read_b128 v[188:191], v139
	ds_read_b128 v[208:211], v139 offset:1024
	ds_read_b128 v[212:215], v139 offset:2048
	ds_read_b128 v[216:219], v139 offset:3072
	ds_read_b128 v[220:223], v139 offset:4096
	ds_read_b128 v[224:227], v139 offset:5120
	ds_read_b128 v[228:231], v139 offset:6144
	ds_read_b128 v[232:235], v139 offset:7168
	global_load_lds_dwordx4 v[192:193], off
	v_lshl_add_u64 v[192:193], s[12:13], 0, v[154:155]
	s_add_i32 m0, s19, 0xe000
	s_nop 0
	global_load_lds_dwordx4 v[192:193], off
	s_cmp_eq_i32 s44, -2
	s_cbranch_scc1 .Lfi_skip8
	s_waitcnt vmcnt(8)
.Lfi_skip8:
	s_waitcnt lgkmcnt(0)
	s_barrier
	s_setprio 1
	s_waitcnt lgkmcnt(0)
	v_mfma_f32_16x16x32_bf16 v[126:129], v[156:159], v[188:191], v[126:129]
	v_mfma_f32_16x16x32_bf16 v[122:125], v[164:167], v[188:191], v[122:125]
	v_mfma_f32_16x16x32_bf16 v[110:113], v[156:159], v[212:215], v[110:113]
	v_mfma_f32_16x16x32_bf16 v[106:109], v[164:167], v[212:215], v[106:109]
	v_mfma_f32_16x16x32_bf16 v[94:97], v[156:159], v[220:223], v[94:97]
	v_mfma_f32_16x16x32_bf16 v[90:93], v[164:167], v[220:223], v[90:93]
	v_mfma_f32_16x16x32_bf16 v[78:81], v[156:159], v[228:231], v[78:81]
	v_mfma_f32_16x16x32_bf16 v[74:77], v[164:167], v[228:231], v[74:77]
	v_mfma_f32_16x16x32_bf16 v[126:129], v[160:163], v[208:211], v[126:129]
	v_mfma_f32_16x16x32_bf16 v[122:125], v[168:171], v[208:211], v[122:125]
	v_mfma_f32_16x16x32_bf16 v[110:113], v[160:163], v[216:219], v[110:113]
	v_mfma_f32_16x16x32_bf16 v[106:109], v[168:171], v[216:219], v[106:109]
	v_mfma_f32_16x16x32_bf16 v[94:97], v[160:163], v[224:227], v[94:97]
	v_mfma_f32_16x16x32_bf16 v[90:93], v[168:171], v[224:227], v[90:93]
	v_mfma_f32_16x16x32_bf16 v[78:81], v[160:163], v[232:235], v[78:81]
	v_mfma_f32_16x16x32_bf16 v[74:77], v[168:171], v[232:235], v[74:77]
	s_setprio 0
	s_setprio 1
	v_mfma_f32_16x16x32_bf16 v[118:121], v[172:175], v[188:191], v[118:121]
	v_mfma_f32_16x16x32_bf16 v[114:117], v[180:183], v[188:191], v[114:117]
	v_mfma_f32_16x16x32_bf16 v[102:105], v[172:175], v[212:215], v[102:105]
	v_mfma_f32_16x16x32_bf16 v[98:101], v[180:183], v[212:215], v[98:101]
	v_mfma_f32_16x16x32_bf16 v[86:89], v[172:175], v[220:223], v[86:89]
	v_mfma_f32_16x16x32_bf16 v[82:85], v[180:183], v[220:223], v[82:85]
	v_mfma_f32_16x16x32_bf16 v[70:73], v[172:175], v[228:231], v[70:73]
	v_mfma_f32_16x16x32_bf16 v[66:69], v[180:183], v[228:231], v[66:69]
	v_mfma_f32_16x16x32_bf16 v[118:121], v[176:179], v[208:211], v[118:121]
	v_mfma_f32_16x16x32_bf16 v[114:117], v[184:187], v[208:211], v[114:117]
	v_mfma_f32_16x16x32_bf16 v[102:105], v[176:179], v[216:219], v[102:105]
	v_mfma_f32_16x16x32_bf16 v[98:101], v[184:187], v[216:219], v[98:101]
	v_mfma_f32_16x16x32_bf16 v[86:89], v[176:179], v[224:227], v[86:89]
	v_mfma_f32_16x16x32_bf16 v[82:85], v[184:187], v[224:227], v[82:85]
	v_mfma_f32_16x16x32_bf16 v[70:73], v[176:179], v[232:235], v[70:73]
	v_mfma_f32_16x16x32_bf16 v[66:69], v[184:187], v[232:235], v[66:69]
	s_setprio 0
	s_barrier
	s_add_i32 s34, s34, s46
	v_lshl_add_u64 v[192:193], s[16:17], 0, v[130:131]
	s_mov_b32 m0, s34
	ds_read_b128 v[188:191], v139 offset:16384
	ds_read_b128 v[208:211], v139 offset:17408
	ds_read_b128 v[212:215], v139 offset:18432
	ds_read_b128 v[216:219], v139 offset:19456
	ds_read_b128 v[220:223], v139 offset:20480
	ds_read_b128 v[224:227], v139 offset:21504
	ds_read_b128 v[228:231], v139 offset:22528
	ds_read_b128 v[232:235], v139 offset:23552
	global_load_lds_dwordx4 v[192:193], off
	s_add_i32 m0, s34, 0x2000
	s_add_u32 s34, s16, 0x40000
	v_lshl_add_u64 v[204:205], s[16:17], 0, v[132:133]
	s_addc_u32 s35, s17, 0
	s_add_i32 s45, s45, s46
	global_load_lds_dwordx4 v[204:205], off
	v_lshl_add_u64 v[236:237], s[34:35], 0, v[130:131]
	s_mov_b32 m0, s45
	v_lshl_add_u64 v[238:239], s[8:9], 0, v[132:133]
	global_load_lds_dwordx4 v[236:237], off
	v_lshl_add_u64 v[236:237], s[34:35], 0, v[132:133]
	s_add_i32 m0, s45, 0x2000
	s_nop 0
	global_load_lds_dwordx4 v[236:237], off
	v_lshl_add_u64 v[236:237], s[8:9], 0, v[130:131]
	s_mov_b32 m0, s19
	s_nop 0
	global_load_lds_dwordx4 v[236:237], off
	s_mov_b32 m0, s80
	s_nop 0
	global_load_lds_dwordx4 v[238:239], off
	s_cmp_eq_i32 s44, -2
	s_cbranch_scc1 .Lfi_skip7
	s_waitcnt vmcnt(8)
; #define PG8_STAGE_A(bufoff, gbase, spf) do { _Pragma("unroll") for (int _i = 0; _i < 2; ++_i) \
;         __builtin_amdgcn_global_load_lds((const unsigned*)((const char*)(gbase) + (Epi::SPECIAL_ROWS && (spf) ? voffS[_i] : voffA[_i])), (LAS unsigned*)(lds + (bufoff) + ldsw + _i * 8192), 16, 0, 0); } while (0)
; #define PG8_LDA(dst, b, h) do { _Pragma("unroll") for (int m = 0; m < 4; ++m) _Pragma("unroll") for (int k = 0; k < 2; ++k) dst[m][k] = *(const LAS bf16x8*)(lds + PG8_SA(b, h) + aoff + m * 2048 + k * 1024); } while (0)
; #define PG8_LDB(dst, b, h) do { _Pragma("unroll") for (int n = 0; n < 2; ++n) _Pragma("unroll") for (int k = 0; k < 2; ++k) dst[n][k] = *(const LAS bf16x8*)(lds + PG8_SB(b, h) + boff + n * 2048 + k * 1024); } while (0)
; #define PG8_MMA(ai, bj, At, Bt) do { __builtin_amdgcn_s_setprio(1); _Pragma("unroll") for (int m = 0; m < 4; ++m) _Pragma("unroll") for (int n = 0; n < 2; ++n) _Pragma("unroll") for (int k = 0; k < 2; ++k) \
;         acc[ai][bj][m][n] = __builtin_amdgcn_mfma_f32_16x16x32_bf16(Bt[n][k], At[m][k], acc[ai][bj][m][n], 0, 0, 0); __builtin_amdgcn_s_setprio(0); } while (0)
; #define PG8_WAIT_V(n) asm volatile("s_waitcnt vmcnt(" #n ")" ::: "memory")
; #define PG8_WAIT_L(n) asm volatile("s_waitcnt lgkmcnt(" #n ")" ::: "memory")
; #define PG8_BAR __builtin_amdgcn_s_barrier()
; #define PG8_SCHED __builtin_amdgcn_sched_barrier(0)
; template <class Epi>
; __device__ __forceinline__ void gemm_phase(LAS unsigned char* lds, const Gemm g, const Sched& S, const Epi& E) {
;     ...
;             PG8_WAIT_V(8); PG8_WAIT_L(0); PG8_BAR; PG8_MMA(1, 0, At, B0); PG8_MMA(1, 1, At, B1); PG8_BAR; PG8_SCHED;
;             PG8_LDB(B0, 1, 0); PG8_LDB(B1, 1, 1); PG8_SCHED; PG8_LDA(At, 1, 0); PG8_STAGE_A(PG8_SA(0, 1), a2 + hA2, sp2);
;             PG8_WAIT_V(8); PG8_WAIT_L(0); PG8_BAR; PG8_MMA(0, 0, At, B0); PG8_MMA(0, 1, At, B1); PG8_BAR; PG8_SCHED;
.Lfi_skip7:
	s_waitcnt lgkmcnt(0)
	s_barrier
	s_setprio 1
	s_waitcnt lgkmcnt(0)
	v_mfma_f32_16x16x32_bf16 v[62:65], v[156:159], v[188:191], v[62:65]
	v_mfma_f32_16x16x32_bf16 v[58:61], v[164:167], v[188:191], v[58:61]
	v_mfma_f32_16x16x32_bf16 v[46:49], v[156:159], v[212:215], v[46:49]
	v_mfma_f32_16x16x32_bf16 v[42:45], v[164:167], v[212:215], v[42:45]
	v_mfma_f32_16x16x32_bf16 v[30:33], v[156:159], v[220:223], v[30:33]
	v_mfma_f32_16x16x32_bf16 v[26:29], v[164:167], v[220:223], v[26:29]
	v_mfma_f32_16x16x32_bf16 v[14:17], v[156:159], v[228:231], v[14:17]
	v_mfma_f32_16x16x32_bf16 v[10:13], v[164:167], v[228:231], v[10:13]
	v_mfma_f32_16x16x32_bf16 v[62:65], v[160:163], v[208:211], v[62:65]
	v_mfma_f32_16x16x32_bf16 v[58:61], v[168:171], v[208:211], v[58:61]
	v_mfma_f32_16x16x32_bf16 v[46:49], v[160:163], v[216:219], v[46:49]
	v_mfma_f32_16x16x32_bf16 v[42:45], v[168:171], v[216:219], v[42:45]
	v_mfma_f32_16x16x32_bf16 v[30:33], v[160:163], v[224:227], v[30:33]
	v_mfma_f32_16x16x32_bf16 v[26:29], v[168:171], v[224:227], v[26:29]
	v_mfma_f32_16x16x32_bf16 v[14:17], v[160:163], v[232:235], v[14:17]
	v_mfma_f32_16x16x32_bf16 v[10:13], v[168:171], v[232:235], v[10:13]
	s_setprio 0
	s_setprio 1
	v_mfma_f32_16x16x32_bf16 v[54:57], v[172:175], v[188:191], v[54:57]
	v_mfma_f32_16x16x32_bf16 v[50:53], v[180:183], v[188:191], v[50:53]
	v_mfma_f32_16x16x32_bf16 v[38:41], v[172:175], v[212:215], v[38:41]
	v_mfma_f32_16x16x32_bf16 v[34:37], v[180:183], v[212:215], v[34:37]
	v_mfma_f32_16x16x32_bf16 v[22:25], v[172:175], v[220:223], v[22:25]
	v_mfma_f32_16x16x32_bf16 v[18:21], v[180:183], v[220:223], v[18:21]
	v_mfma_f32_16x16x32_bf16 v[6:9], v[172:175], v[228:231], v[6:9]
	v_mfma_f32_16x16x32_bf16 v[2:5], v[180:183], v[228:231], v[2:5]
	v_mfma_f32_16x16x32_bf16 v[54:57], v[176:179], v[208:211], v[54:57]
	v_mfma_f32_16x16x32_bf16 v[50:53], v[184:187], v[208:211], v[50:53]
	v_mfma_f32_16x16x32_bf16 v[38:41], v[176:179], v[216:219], v[38:41]
	v_mfma_f32_16x16x32_bf16 v[34:37], v[184:187], v[216:219], v[34:37]
	v_mfma_f32_16x16x32_bf16 v[22:25], v[176:179], v[224:227], v[22:25]
	v_mfma_f32_16x16x32_bf16 v[18:21], v[184:187], v[224:227], v[18:21]
	v_mfma_f32_16x16x32_bf16 v[6:9], v[176:179], v[232:235], v[6:9]
	v_mfma_f32_16x16x32_bf16 v[2:5], v[184:187], v[232:235], v[2:5]
	s_setprio 0
	s_barrier
	s_add_i32 s34, 0, 0x18000
	v_add_u32_e32 v0, s34, v135
	s_add_i32 s35, 0, 0x1c000
	ds_read_b128 v[156:159], v0
	ds_read_b128 v[160:163], v0 offset:1024
	ds_read_b128 v[164:167], v0 offset:2048
	ds_read_b128 v[168:171], v0 offset:3072
	v_add_u32_e32 v0, s35, v135
	ds_read_b128 v[172:175], v0
	ds_read_b128 v[176:179], v0 offset:1024
	ds_read_b128 v[180:183], v0 offset:2048
	ds_read_b128 v[184:187], v0 offset:3072
	s_add_u32 s8, s8, 0x40000
	s_addc_u32 s9, s9, 0
	s_mov_b32 m0, s81
	v_lshl_add_u64 v[240:241], s[8:9], 0, v[130:131]
	ds_read_b128 v[188:191], v139 offset:32768
	ds_read_b128 v[208:211], v139 offset:33792
	ds_read_b128 v[212:215], v139 offset:34816
	ds_read_b128 v[216:219], v139 offset:35840
	ds_read_b128 v[220:223], v139 offset:36864
	ds_read_b128 v[224:227], v139 offset:37888
	ds_read_b128 v[228:231], v139 offset:38912
	ds_read_b128 v[232:235], v139 offset:39936
	global_load_lds_dwordx4 v[240:241], off
	v_lshl_add_u64 v[240:241], s[8:9], 0, v[132:133]
	s_mov_b32 m0, s82
	s_nop 0
	global_load_lds_dwordx4 v[240:241], off
	s_waitcnt vmcnt(8)
	s_waitcnt lgkmcnt(0)
	s_barrier
	s_setprio 1
	s_waitcnt lgkmcnt(0)
	v_mfma_f32_16x16x32_bf16 v[126:129], v[156:159], v[188:191], v[126:129]
	v_mfma_f32_16x16x32_bf16 v[122:125], v[164:167], v[188:191], v[122:125]
	v_mfma_f32_16x16x32_bf16 v[110:113], v[156:159], v[212:215], v[110:113]
	v_mfma_f32_16x16x32_bf16 v[106:109], v[164:167], v[212:215], v[106:109]
	v_mfma_f32_16x16x32_bf16 v[94:97], v[156:159], v[220:223], v[94:97]
	v_mfma_f32_16x16x32_bf16 v[90:93], v[164:167], v[220:223], v[90:93]
	v_mfma_f32_16x16x32_bf16 v[78:81], v[156:159], v[228:231], v[78:81]
	v_mfma_f32_16x16x32_bf16 v[74:77], v[164:167], v[228:231], v[74:77]
	v_mfma_f32_16x16x32_bf16 v[126:129], v[160:163], v[208:211], v[126:129]
	v_mfma_f32_16x16x32_bf16 v[122:125], v[168:171], v[208:211], v[122:125]
	v_mfma_f32_16x16x32_bf16 v[110:113], v[160:163], v[216:219], v[110:113]
	v_mfma_f32_16x16x32_bf16 v[106:109], v[168:171], v[216:219], v[106:109]
	v_mfma_f32_16x16x32_bf16 v[94:97], v[160:163], v[224:227], v[94:97]
	v_mfma_f32_16x16x32_bf16 v[90:93], v[168:171], v[224:227], v[90:93]
	v_mfma_f32_16x16x32_bf16 v[78:81], v[160:163], v[232:235], v[78:81]
	v_mfma_f32_16x16x32_bf16 v[74:77], v[168:171], v[232:235], v[74:77]
	s_setprio 0
	s_setprio 1
	v_mfma_f32_16x16x32_bf16 v[118:121], v[172:175], v[188:191], v[118:121]
	v_mfma_f32_16x16x32_bf16 v[114:117], v[180:183], v[188:191], v[114:117]
	v_mfma_f32_16x16x32_bf16 v[102:105], v[172:175], v[212:215], v[102:105]
	v_mfma_f32_16x16x32_bf16 v[98:101], v[180:183], v[212:215], v[98:101]
	v_mfma_f32_16x16x32_bf16 v[86:89], v[172:175], v[220:223], v[86:89]
	v_mfma_f32_16x16x32_bf16 v[82:85], v[180:183], v[220:223], v[82:85]
	v_mfma_f32_16x16x32_bf16 v[70:73], v[172:175], v[228:231], v[70:73]
	v_mfma_f32_16x16x32_bf16 v[66:69], v[180:183], v[228:231], v[66:69]
	v_mfma_f32_16x16x32_bf16 v[118:121], v[176:179], v[208:211], v[118:121]
	v_mfma_f32_16x16x32_bf16 v[114:117], v[184:187], v[208:211], v[114:117]
	v_mfma_f32_16x16x32_bf16 v[102:105], v[176:179], v[216:219], v[102:105]
	v_mfma_f32_16x16x32_bf16 v[98:101], v[184:187], v[216:219], v[98:101]
	v_mfma_f32_16x16x32_bf16 v[86:89], v[176:179], v[224:227], v[86:89]
	v_mfma_f32_16x16x32_bf16 v[82:85], v[184:187], v[224:227], v[82:85]
	v_mfma_f32_16x16x32_bf16 v[70:73], v[176:179], v[232:235], v[70:73]
	v_mfma_f32_16x16x32_bf16 v[66:69], v[184:187], v[232:235], v[66:69]
	s_setprio 0
	s_barrier
; #define PG8_STAGE(bufoff, gbase, voff) do { _Pragma("unroll") for (int _i = 0; _i < 2; ++_i) \
;         __builtin_amdgcn_global_load_lds((const unsigned*)((const char*)(gbase) + (voff)[_i]), (LAS unsigned*)(lds + (bufoff) + ldsw + _i * 8192), 16, 0, 0); } while (0)
; #define PG8_STAGE_A(bufoff, gbase, spf) do { _Pragma("unroll") for (int _i = 0; _i < 2; ++_i) \
;         __builtin_amdgcn_global_load_lds((const unsigned*)((const char*)(gbase) + (Epi::SPECIAL_ROWS && (spf) ? voffS[_i] : voffA[_i])), (LAS unsigned*)(lds + (bufoff) + ldsw + _i * 8192), 16, 0, 0); } while (0)
; #define PG8_LDA(dst, b, h) do { _Pragma("unroll") for (int m = 0; m < 4; ++m) _Pragma("unroll") for (int k = 0; k < 2; ++k) dst[m][k] = *(const LAS bf16x8*)(lds + PG8_SA(b, h) + aoff + m * 2048 + k * 1024); } while (0)
; #define PG8_MMA(ai, bj, At, Bt) do { __builtin_amdgcn_s_setprio(1); _Pragma("unroll") for (int m = 0; m < 4; ++m) _Pragma("unroll") for (int n = 0; n < 2; ++n) _Pragma("unroll") for (int k = 0; k < 2; ++k) \
;         acc[ai][bj][m][n] = __builtin_amdgcn_mfma_f32_16x16x32_bf16(Bt[n][k], At[m][k], acc[ai][bj][m][n], 0, 0, 0); __builtin_amdgcn_s_setprio(0); } while (0)
; #define PG8_WAIT_V(n) asm volatile("s_waitcnt vmcnt(" #n ")" ::: "memory")
; #define PG8_WAIT_L(n) asm volatile("s_waitcnt lgkmcnt(" #n ")" ::: "memory")
; #define PG8_BAR __builtin_amdgcn_s_barrier()
; #define PG8_SCHED __builtin_amdgcn_sched_barrier(0)
; template <class Epi>
; __device__ __forceinline__ void gemm_phase(LAS unsigned char* lds, const Gemm g, const Sched& S, const Epi& E) {
;     ...
;             PG8_LDA(At, 1, 1); PG8_STAGE(PG8_SB(1, 0), b3, voffB); PG8_STAGE(PG8_SB(1, 1), b3 + hstepB, voffB); PG8_STAGE_A(PG8_SA(1, 0), a3, sp2);
;             PG8_WAIT_V(8); PG8_WAIT_L(0); PG8_BAR; PG8_MMA(1, 0, At, B0); PG8_MMA(1, 1, At, B1); PG8_BAR; PG8_SCHED;
;         }
;         if (wr == 0) PG8_BAR;
	s_add_i32 s8, s34, s46
	v_lshl_add_u64 v[192:193], v[192:193], 0, s[20:21]
	s_mov_b32 m0, s8
	ds_read_b128 v[188:191], v139 offset:49152
	ds_read_b128 v[208:211], v139 offset:50176
	ds_read_b128 v[212:215], v139 offset:51200
	ds_read_b128 v[216:219], v139 offset:52224
	ds_read_b128 v[220:223], v139 offset:53248
	ds_read_b128 v[224:227], v139 offset:54272
	ds_read_b128 v[228:231], v139 offset:55296
	ds_read_b128 v[232:235], v139 offset:56320
	global_load_lds_dwordx4 v[192:193], off
	s_add_i32 m0, s8, 0x2000
	s_add_u32 s8, s16, 0x40080
	v_lshl_add_u64 v[192:193], v[204:205], 0, s[20:21]
	s_addc_u32 s9, s17, 0
	s_add_i32 s16, s35, s46
	global_load_lds_dwordx4 v[192:193], off
	v_lshl_add_u64 v[192:193], s[8:9], 0, v[130:131]
	s_mov_b32 m0, s16
	s_nop 0
	global_load_lds_dwordx4 v[192:193], off
	v_lshl_add_u64 v[192:193], s[8:9], 0, v[132:133]
	s_add_i32 m0, s16, 0x2000
	s_nop 0
	global_load_lds_dwordx4 v[192:193], off
	v_lshl_add_u64 v[192:193], v[236:237], 0, s[20:21]
	s_mov_b32 m0, s83
	s_nop 0
	global_load_lds_dwordx4 v[192:193], off
	v_lshl_add_u64 v[192:193], v[238:239], 0, s[20:21]
	s_mov_b32 m0, s84
	s_nop 0
	global_load_lds_dwordx4 v[192:193], off
	s_waitcnt vmcnt(8)
	s_waitcnt lgkmcnt(0)
	s_barrier
	s_setprio 1
	s_waitcnt lgkmcnt(0)
	v_mfma_f32_16x16x32_bf16 v[62:65], v[156:159], v[188:191], v[62:65]
	v_mfma_f32_16x16x32_bf16 v[58:61], v[164:167], v[188:191], v[58:61]
	v_mfma_f32_16x16x32_bf16 v[46:49], v[156:159], v[212:215], v[46:49]
	v_mfma_f32_16x16x32_bf16 v[42:45], v[164:167], v[212:215], v[42:45]
	v_mfma_f32_16x16x32_bf16 v[30:33], v[156:159], v[220:223], v[30:33]
	v_mfma_f32_16x16x32_bf16 v[26:29], v[164:167], v[220:223], v[26:29]
	v_mfma_f32_16x16x32_bf16 v[14:17], v[156:159], v[228:231], v[14:17]
	v_mfma_f32_16x16x32_bf16 v[10:13], v[164:167], v[228:231], v[10:13]
	v_mfma_f32_16x16x32_bf16 v[62:65], v[160:163], v[208:211], v[62:65]
	v_mfma_f32_16x16x32_bf16 v[58:61], v[168:171], v[208:211], v[58:61]
	v_mfma_f32_16x16x32_bf16 v[46:49], v[160:163], v[216:219], v[46:49]
	v_mfma_f32_16x16x32_bf16 v[42:45], v[168:171], v[216:219], v[42:45]
	v_mfma_f32_16x16x32_bf16 v[30:33], v[160:163], v[224:227], v[30:33]
	v_mfma_f32_16x16x32_bf16 v[26:29], v[168:171], v[224:227], v[26:29]
	v_mfma_f32_16x16x32_bf16 v[14:17], v[160:163], v[232:235], v[14:17]
	v_mfma_f32_16x16x32_bf16 v[10:13], v[168:171], v[232:235], v[10:13]
	s_setprio 0
	s_setprio 1
	v_mfma_f32_16x16x32_bf16 v[54:57], v[172:175], v[188:191], v[54:57]
	v_mfma_f32_16x16x32_bf16 v[50:53], v[180:183], v[188:191], v[50:53]
	v_mfma_f32_16x16x32_bf16 v[38:41], v[172:175], v[212:215], v[38:41]
	v_mfma_f32_16x16x32_bf16 v[34:37], v[180:183], v[212:215], v[34:37]
	v_mfma_f32_16x16x32_bf16 v[22:25], v[172:175], v[220:223], v[22:25]
	v_mfma_f32_16x16x32_bf16 v[18:21], v[180:183], v[220:223], v[18:21]
	v_mfma_f32_16x16x32_bf16 v[6:9], v[172:175], v[228:231], v[6:9]
	v_mfma_f32_16x16x32_bf16 v[2:5], v[180:183], v[228:231], v[2:5]
	v_mfma_f32_16x16x32_bf16 v[54:57], v[176:179], v[208:211], v[54:57]
	v_mfma_f32_16x16x32_bf16 v[50:53], v[184:187], v[208:211], v[50:53]
	v_mfma_f32_16x16x32_bf16 v[38:41], v[176:179], v[216:219], v[38:41]
	v_mfma_f32_16x16x32_bf16 v[34:37], v[184:187], v[216:219], v[34:37]
	v_mfma_f32_16x16x32_bf16 v[22:25], v[176:179], v[224:227], v[22:25]
	v_mfma_f32_16x16x32_bf16 v[18:21], v[184:187], v[224:227], v[18:21]
	v_mfma_f32_16x16x32_bf16 v[6:9], v[176:179], v[232:235], v[6:9]
	v_mfma_f32_16x16x32_bf16 v[2:5], v[184:187], v[232:235], v[2:5]
	s_setprio 0
	s_barrier
	s_add_i32 s44, s44, 2
	s_add_u32 s12, s12, 0x100
	s_addc_u32 s13, s13, 0
	s_add_u32 s42, s42, 0x100
	s_addc_u32 s43, s43, 0
	s_cmp_gt_u32 s44, 13
	s_cbranch_scc0 .LBB0_637
	s_and_b64 vcc, exec, s[68:69]
	s_cbranch_vccz .LBB0_640
	s_barrier

; #define PG8_STAGE(bufoff, gbase, voff) do { _Pragma("unroll") for (int _i = 0; _i < 2; ++_i) \
;         __builtin_amdgcn_global_load_lds((const unsigned*)((const char*)(gbase) + (voff)[_i]), (LAS unsigned*)(lds + (bufoff) + ldsw + _i * 8192), 16, 0, 0); } while (0)
; #define PG8_STAGE_A(bufoff, gbase, spf) do { _Pragma("unroll") for (int _i = 0; _i < 2; ++_i) \
;         __builtin_amdgcn_global_load_lds((const unsigned*)((const char*)(gbase) + (Epi::SPECIAL_ROWS && (spf) ? voffS[_i] : voffA[_i])), (LAS unsigned*)(lds + (bufoff) + ldsw + _i * 8192), 16, 0, 0); } while (0)
; #define PG8_LDA(dst, b, h) do { _Pragma("unroll") for (int m = 0; m < 4; ++m) _Pragma("unroll") for (int k = 0; k < 2; ++k) dst[m][k] = *(const LAS bf16x8*)(lds + PG8_SA(b, h) + aoff + m * 2048 + k * 1024); } while (0)
; #define PG8_LDB(dst, b, h) do { _Pragma("unroll") for (int n = 0; n < 2; ++n) _Pragma("unroll") for (int k = 0; k < 2; ++k) dst[n][k] = *(const LAS bf16x8*)(lds + PG8_SB(b, h) + boff + n * 2048 + k * 1024); } while (0)
; #define PG8_WAIT_V(n) asm volatile("s_waitcnt vmcnt(" #n ")" ::: "memory")
; #define PG8_WAIT_L(n) asm volatile("s_waitcnt lgkmcnt(" #n ")" ::: "memory")
; #define PG8_BAR __builtin_amdgcn_s_barrier()
; template <class Epi>
; __device__ __forceinline__ void gemm_phase(LAS unsigned char* lds, const Gemm g, const Sched& S, const Epi& E) {
;     ...
;         for (int t = 0; t < nt; t += 2) {
;             const bool last = (t == nt - 2);
;             const char* a1 = cA + (size_t)((t + 1) & kmask) * kstep;
;             const char* a2 = last ? nA : cA + (size_t)((t + 2) & kmask) * kstep; const char* b2 = last ? nB : cB + (size_t)((t + 2) & kmask) * kstep;
;             const char* a3 = a2 + kstep; const char* b3 = b2 + kstep;
;             const bool sp2 = last ? nsp : csp; const size_t hA2 = last ? nhA : chA;
;             PG8_LDB(B0, 0, 0); PG8_LDB(B1, 0, 1); PG8_SCHED; PG8_LDA(At, 0, 0); PG8_STAGE_A(PG8_SA(1, 1), a1 + chA, csp);
;             PG8_WAIT_V(8); PG8_WAIT_L(0); PG8_BAR; PG8_MMA(0, 0, At, B0); PG8_MMA(0, 1, At, B1); PG8_BAR; PG8_SCHED;
;             PG8_LDA(At, 0, 1); PG8_STAGE(PG8_SB(0, 0), b2, voffB); PG8_STAGE(PG8_SB(0, 1), b2 + hstepB, voffB); PG8_STAGE_A(PG8_SA(0, 0), a2, sp2);
;             PG8_WAIT_V(8); PG8_WAIT_L(0); PG8_BAR; PG8_MMA(1, 0, At, B0); PG8_MMA(1, 1, At, B1); PG8_BAR; PG8_SCHED;
.LBB0_1023:
	s_add_u32 s42, s34, 0x100
	s_addc_u32 s43, s35, 0
	s_add_i32 s65, 0, 0x10000
	s_cmp_eq_u32 s31, 40
	s_cselect_b32 s9, s1, s43
	s_cselect_b32 s8, s0, s42
	s_cselect_b32 s23, s19, s30
	s_cselect_b32 s22, s18, s13
	s_add_i32 s66, 0, 0x14000
	v_add_u32_e32 v142, s65, v178
	v_add_u32_e32 v166, s66, v178
	ds_read_b128 v[130:133], v142
	ds_read_b128 v[134:137], v142 offset:1024
	ds_read_b128 v[138:141], v142 offset:2048
	ds_read_b128 v[142:145], v142 offset:3072
	ds_read_b128 v[146:149], v166
	ds_read_b128 v[150:153], v166 offset:1024
	ds_read_b128 v[154:157], v166 offset:2048
	ds_read_b128 v[166:169], v166 offset:3072
	v_lshl_add_u64 v[200:201], s[34:35], 0, v[162:163]
	s_add_i32 m0, s45, 0xc000
	ds_read_b128 v[170:173], v180
	ds_read_b128 v[174:177], v180 offset:1024
	ds_read_b128 v[182:185], v180 offset:2048
	ds_read_b128 v[186:189], v180 offset:3072
	ds_read_b128 v[190:193], v180 offset:4096
	ds_read_b128 v[208:211], v180 offset:5120
	ds_read_b128 v[212:215], v180 offset:6144
	ds_read_b128 v[216:219], v180 offset:7168
	global_load_lds_dwordx4 v[200:201], off
	v_lshl_add_u64 v[200:201], s[34:35], 0, v[164:165]
	s_add_i32 m0, s45, 0xe000
	s_nop 0
	global_load_lds_dwordx4 v[200:201], off
	s_cmp_eq_i32 s31, -2
	s_cbranch_scc1 .Lfi_skip10
	s_waitcnt vmcnt(8)
.Lfi_skip10:
	s_waitcnt lgkmcnt(0)
	s_barrier
	s_setprio 1
	s_waitcnt lgkmcnt(0)
	v_mfma_f32_16x16x32_bf16 v[126:129], v[130:133], v[170:173], v[126:129]
	v_mfma_f32_16x16x32_bf16 v[122:125], v[138:141], v[170:173], v[122:125]
	v_mfma_f32_16x16x32_bf16 v[110:113], v[130:133], v[182:185], v[110:113]
	v_mfma_f32_16x16x32_bf16 v[106:109], v[138:141], v[182:185], v[106:109]
	v_mfma_f32_16x16x32_bf16 v[94:97], v[130:133], v[190:193], v[94:97]
	v_mfma_f32_16x16x32_bf16 v[90:93], v[138:141], v[190:193], v[90:93]
	v_mfma_f32_16x16x32_bf16 v[78:81], v[130:133], v[212:215], v[78:81]
	v_mfma_f32_16x16x32_bf16 v[74:77], v[138:141], v[212:215], v[74:77]
	v_mfma_f32_16x16x32_bf16 v[126:129], v[134:137], v[174:177], v[126:129]
	v_mfma_f32_16x16x32_bf16 v[122:125], v[142:145], v[174:177], v[122:125]
	v_mfma_f32_16x16x32_bf16 v[110:113], v[134:137], v[186:189], v[110:113]
	v_mfma_f32_16x16x32_bf16 v[106:109], v[142:145], v[186:189], v[106:109]
	v_mfma_f32_16x16x32_bf16 v[94:97], v[134:137], v[208:211], v[94:97]
	v_mfma_f32_16x16x32_bf16 v[90:93], v[142:145], v[208:211], v[90:93]
	v_mfma_f32_16x16x32_bf16 v[78:81], v[134:137], v[216:219], v[78:81]
	v_mfma_f32_16x16x32_bf16 v[74:77], v[142:145], v[216:219], v[74:77]
	s_setprio 0
	s_setprio 1
	v_mfma_f32_16x16x32_bf16 v[118:121], v[146:149], v[170:173], v[118:121]
	v_mfma_f32_16x16x32_bf16 v[114:117], v[154:157], v[170:173], v[114:117]
	v_mfma_f32_16x16x32_bf16 v[102:105], v[146:149], v[182:185], v[102:105]
	v_mfma_f32_16x16x32_bf16 v[98:101], v[154:157], v[182:185], v[98:101]
	v_mfma_f32_16x16x32_bf16 v[86:89], v[146:149], v[190:193], v[86:89]
	v_mfma_f32_16x16x32_bf16 v[82:85], v[154:157], v[190:193], v[82:85]
	v_mfma_f32_16x16x32_bf16 v[70:73], v[146:149], v[212:215], v[70:73]
	v_mfma_f32_16x16x32_bf16 v[66:69], v[154:157], v[212:215], v[66:69]
	v_mfma_f32_16x16x32_bf16 v[118:121], v[150:153], v[174:177], v[118:121]
	v_mfma_f32_16x16x32_bf16 v[114:117], v[166:169], v[174:177], v[114:117]
	v_mfma_f32_16x16x32_bf16 v[102:105], v[150:153], v[186:189], v[102:105]
	v_mfma_f32_16x16x32_bf16 v[98:101], v[166:169], v[186:189], v[98:101]
	v_mfma_f32_16x16x32_bf16 v[86:89], v[150:153], v[208:211], v[86:89]
	v_mfma_f32_16x16x32_bf16 v[82:85], v[166:169], v[208:211], v[82:85]
	v_mfma_f32_16x16x32_bf16 v[70:73], v[150:153], v[216:219], v[70:73]
	v_mfma_f32_16x16x32_bf16 v[66:69], v[166:169], v[216:219], v[66:69]
	s_setprio 0
	s_barrier
	s_add_i32 s34, s65, s44
	v_lshl_add_u64 v[200:201], s[22:23], 0, v[0:1]
	s_mov_b32 m0, s34
	ds_read_b128 v[170:173], v180 offset:16384
	ds_read_b128 v[174:177], v180 offset:17408
	ds_read_b128 v[182:185], v180 offset:18432
	ds_read_b128 v[186:189], v180 offset:19456
	ds_read_b128 v[190:193], v180 offset:20480
	ds_read_b128 v[208:211], v180 offset:21504
	ds_read_b128 v[212:215], v180 offset:22528
	ds_read_b128 v[216:219], v180 offset:23552
	global_load_lds_dwordx4 v[200:201], off
	s_add_i32 m0, s34, 0x2000
	s_add_u32 s34, s22, 0xb0000
	v_lshl_add_u64 v[202:203], s[22:23], 0, v[158:159]
	s_addc_u32 s35, s23, 0
	s_add_i32 s65, s66, s44
	global_load_lds_dwordx4 v[202:203], off
	v_lshl_add_u64 v[204:205], s[34:35], 0, v[0:1]
	s_mov_b32 m0, s65
	v_lshl_add_u64 v[206:207], s[8:9], 0, v[158:159]
	global_load_lds_dwordx4 v[204:205], off
	v_lshl_add_u64 v[204:205], s[34:35], 0, v[158:159]
	s_add_i32 m0, s65, 0x2000
	s_nop 0
	global_load_lds_dwordx4 v[204:205], off
	v_lshl_add_u64 v[204:205], s[8:9], 0, v[0:1]
	s_mov_b32 m0, s45
	s_nop 0
	global_load_lds_dwordx4 v[204:205], off
	s_mov_b32 m0, s46
	s_nop 0
	global_load_lds_dwordx4 v[206:207], off
	s_cmp_eq_i32 s31, -2
	s_cbranch_scc1 .Lfi_skip9
	s_waitcnt vmcnt(8)
; #define PG8_STAGE_A(bufoff, gbase, spf) do { _Pragma("unroll") for (int _i = 0; _i < 2; ++_i) \
;         __builtin_amdgcn_global_load_lds((const unsigned*)((const char*)(gbase) + (Epi::SPECIAL_ROWS && (spf) ? voffS[_i] : voffA[_i])), (LAS unsigned*)(lds + (bufoff) + ldsw + _i * 8192), 16, 0, 0); } while (0)
; #define PG8_LDA(dst, b, h) do { _Pragma("unroll") for (int m = 0; m < 4; ++m) _Pragma("unroll") for (int k = 0; k < 2; ++k) dst[m][k] = *(const LAS bf16x8*)(lds + PG8_SA(b, h) + aoff + m * 2048 + k * 1024); } while (0)
; #define PG8_LDB(dst, b, h) do { _Pragma("unroll") for (int n = 0; n < 2; ++n) _Pragma("unroll") for (int k = 0; k < 2; ++k) dst[n][k] = *(const LAS bf16x8*)(lds + PG8_SB(b, h) + boff + n * 2048 + k * 1024); } while (0)
; #define PG8_MMA(ai, bj, At, Bt) do { __builtin_amdgcn_s_setprio(1); _Pragma("unroll") for (int m = 0; m < 4; ++m) _Pragma("unroll") for (int n = 0; n < 2; ++n) _Pragma("unroll") for (int k = 0; k < 2; ++k) \
;         acc[ai][bj][m][n] = __builtin_amdgcn_mfma_f32_16x16x32_bf16(Bt[n][k], At[m][k], acc[ai][bj][m][n], 0, 0, 0); __builtin_amdgcn_s_setprio(0); } while (0)
; #define PG8_WAIT_V(n) asm volatile("s_waitcnt vmcnt(" #n ")" ::: "memory")
; #define PG8_WAIT_L(n) asm volatile("s_waitcnt lgkmcnt(" #n ")" ::: "memory")
; #define PG8_BAR __builtin_amdgcn_s_barrier()
; #define PG8_SCHED __builtin_amdgcn_sched_barrier(0)
; template <class Epi>
; __device__ __forceinline__ void gemm_phase(LAS unsigned char* lds, const Gemm g, const Sched& S, const Epi& E) {
;     ...
;             PG8_WAIT_V(8); PG8_WAIT_L(0); PG8_BAR; PG8_MMA(1, 0, At, B0); PG8_MMA(1, 1, At, B1); PG8_BAR; PG8_SCHED;
;             PG8_LDB(B0, 1, 0); PG8_LDB(B1, 1, 1); PG8_SCHED; PG8_LDA(At, 1, 0); PG8_STAGE_A(PG8_SA(0, 1), a2 + hA2, sp2);
;             PG8_WAIT_V(8); PG8_WAIT_L(0); PG8_BAR; PG8_MMA(0, 0, At, B0); PG8_MMA(0, 1, At, B1); PG8_BAR; PG8_SCHED;
.Lfi_skip9:
	s_waitcnt lgkmcnt(0)
	s_barrier
	s_setprio 1
	s_waitcnt lgkmcnt(0)
	v_mfma_f32_16x16x32_bf16 v[62:65], v[130:133], v[170:173], v[62:65]
	v_mfma_f32_16x16x32_bf16 v[58:61], v[138:141], v[170:173], v[58:61]
	v_mfma_f32_16x16x32_bf16 v[46:49], v[130:133], v[182:185], v[46:49]
	v_mfma_f32_16x16x32_bf16 v[42:45], v[138:141], v[182:185], v[42:45]
	v_mfma_f32_16x16x32_bf16 v[30:33], v[130:133], v[190:193], v[30:33]
	v_mfma_f32_16x16x32_bf16 v[26:29], v[138:141], v[190:193], v[26:29]
	v_mfma_f32_16x16x32_bf16 v[14:17], v[130:133], v[212:215], v[14:17]
	v_mfma_f32_16x16x32_bf16 v[10:13], v[138:141], v[212:215], v[10:13]
	v_mfma_f32_16x16x32_bf16 v[62:65], v[134:137], v[174:177], v[62:65]
	v_mfma_f32_16x16x32_bf16 v[58:61], v[142:145], v[174:177], v[58:61]
	v_mfma_f32_16x16x32_bf16 v[46:49], v[134:137], v[186:189], v[46:49]
	v_mfma_f32_16x16x32_bf16 v[42:45], v[142:145], v[186:189], v[42:45]
	v_mfma_f32_16x16x32_bf16 v[30:33], v[134:137], v[208:211], v[30:33]
	v_mfma_f32_16x16x32_bf16 v[26:29], v[142:145], v[208:211], v[26:29]
	v_mfma_f32_16x16x32_bf16 v[14:17], v[134:137], v[216:219], v[14:17]
	v_mfma_f32_16x16x32_bf16 v[10:13], v[142:145], v[216:219], v[10:13]
	s_setprio 0
	s_setprio 1
	v_mfma_f32_16x16x32_bf16 v[54:57], v[146:149], v[170:173], v[54:57]
	v_mfma_f32_16x16x32_bf16 v[50:53], v[154:157], v[170:173], v[50:53]
	v_mfma_f32_16x16x32_bf16 v[38:41], v[146:149], v[182:185], v[38:41]
	v_mfma_f32_16x16x32_bf16 v[34:37], v[154:157], v[182:185], v[34:37]
	v_mfma_f32_16x16x32_bf16 v[22:25], v[146:149], v[190:193], v[22:25]
	v_mfma_f32_16x16x32_bf16 v[18:21], v[154:157], v[190:193], v[18:21]
	v_mfma_f32_16x16x32_bf16 v[6:9], v[146:149], v[212:215], v[6:9]
	v_mfma_f32_16x16x32_bf16 v[2:5], v[154:157], v[212:215], v[2:5]
	v_mfma_f32_16x16x32_bf16 v[54:57], v[150:153], v[174:177], v[54:57]
	v_mfma_f32_16x16x32_bf16 v[50:53], v[166:169], v[174:177], v[50:53]
	v_mfma_f32_16x16x32_bf16 v[38:41], v[150:153], v[186:189], v[38:41]
	v_mfma_f32_16x16x32_bf16 v[34:37], v[166:169], v[186:189], v[34:37]
	v_mfma_f32_16x16x32_bf16 v[22:25], v[150:153], v[208:211], v[22:25]
	v_mfma_f32_16x16x32_bf16 v[18:21], v[166:169], v[208:211], v[18:21]
	v_mfma_f32_16x16x32_bf16 v[6:9], v[150:153], v[216:219], v[6:9]
	v_mfma_f32_16x16x32_bf16 v[2:5], v[166:169], v[216:219], v[2:5]
	s_setprio 0
	s_barrier
	s_add_i32 s34, 0, 0x18000
	s_add_i32 s35, 0, 0x1c000
	v_add_u32_e32 v142, s34, v178
	v_add_u32_e32 v166, s35, v178
	ds_read_b128 v[130:133], v142
	ds_read_b128 v[134:137], v142 offset:1024
	ds_read_b128 v[138:141], v142 offset:2048
	ds_read_b128 v[142:145], v142 offset:3072
	ds_read_b128 v[146:149], v166
	ds_read_b128 v[150:153], v166 offset:1024
	ds_read_b128 v[154:157], v166 offset:2048
	ds_read_b128 v[166:169], v166 offset:3072
	s_add_u32 s8, s8, 0xb0000
	s_addc_u32 s9, s9, 0
	s_mov_b32 m0, s47
	v_lshl_add_u64 v[220:221], s[8:9], 0, v[0:1]
	ds_read_b128 v[170:173], v180 offset:32768
	ds_read_b128 v[174:177], v180 offset:33792
	ds_read_b128 v[182:185], v180 offset:34816
	ds_read_b128 v[186:189], v180 offset:35840
	ds_read_b128 v[190:193], v180 offset:36864
	ds_read_b128 v[208:211], v180 offset:37888
	ds_read_b128 v[212:215], v180 offset:38912
	ds_read_b128 v[216:219], v180 offset:39936
	global_load_lds_dwordx4 v[220:221], off
	v_lshl_add_u64 v[220:221], s[8:9], 0, v[158:159]
	s_mov_b32 m0, s54
	s_nop 0
	global_load_lds_dwordx4 v[220:221], off
	s_waitcnt vmcnt(8)
	s_waitcnt lgkmcnt(0)
	s_barrier
	s_setprio 1
	s_waitcnt lgkmcnt(0)
	v_mfma_f32_16x16x32_bf16 v[126:129], v[130:133], v[170:173], v[126:129]
	v_mfma_f32_16x16x32_bf16 v[122:125], v[138:141], v[170:173], v[122:125]
	v_mfma_f32_16x16x32_bf16 v[110:113], v[130:133], v[182:185], v[110:113]
	v_mfma_f32_16x16x32_bf16 v[106:109], v[138:141], v[182:185], v[106:109]
	v_mfma_f32_16x16x32_bf16 v[94:97], v[130:133], v[190:193], v[94:97]
	v_mfma_f32_16x16x32_bf16 v[90:93], v[138:141], v[190:193], v[90:93]
	v_mfma_f32_16x16x32_bf16 v[78:81], v[130:133], v[212:215], v[78:81]
	v_mfma_f32_16x16x32_bf16 v[74:77], v[138:141], v[212:215], v[74:77]
	v_mfma_f32_16x16x32_bf16 v[126:129], v[134:137], v[174:177], v[126:129]
	v_mfma_f32_16x16x32_bf16 v[122:125], v[142:145], v[174:177], v[122:125]
	v_mfma_f32_16x16x32_bf16 v[110:113], v[134:137], v[186:189], v[110:113]
	v_mfma_f32_16x16x32_bf16 v[106:109], v[142:145], v[186:189], v[106:109]
	v_mfma_f32_16x16x32_bf16 v[94:97], v[134:137], v[208:211], v[94:97]
	v_mfma_f32_16x16x32_bf16 v[90:93], v[142:145], v[208:211], v[90:93]
	v_mfma_f32_16x16x32_bf16 v[78:81], v[134:137], v[216:219], v[78:81]
	v_mfma_f32_16x16x32_bf16 v[74:77], v[142:145], v[216:219], v[74:77]
	s_setprio 0
	s_setprio 1
	v_mfma_f32_16x16x32_bf16 v[118:121], v[146:149], v[170:173], v[118:121]
	v_mfma_f32_16x16x32_bf16 v[114:117], v[154:157], v[170:173], v[114:117]
	v_mfma_f32_16x16x32_bf16 v[102:105], v[146:149], v[182:185], v[102:105]
	v_mfma_f32_16x16x32_bf16 v[98:101], v[154:157], v[182:185], v[98:101]
	v_mfma_f32_16x16x32_bf16 v[86:89], v[146:149], v[190:193], v[86:89]
	v_mfma_f32_16x16x32_bf16 v[82:85], v[154:157], v[190:193], v[82:85]
	v_mfma_f32_16x16x32_bf16 v[70:73], v[146:149], v[212:215], v[70:73]
	v_mfma_f32_16x16x32_bf16 v[66:69], v[154:157], v[212:215], v[66:69]
	v_mfma_f32_16x16x32_bf16 v[118:121], v[150:153], v[174:177], v[118:121]
	v_mfma_f32_16x16x32_bf16 v[114:117], v[166:169], v[174:177], v[114:117]
	v_mfma_f32_16x16x32_bf16 v[102:105], v[150:153], v[186:189], v[102:105]
	v_mfma_f32_16x16x32_bf16 v[98:101], v[166:169], v[186:189], v[98:101]
	v_mfma_f32_16x16x32_bf16 v[86:89], v[150:153], v[208:211], v[86:89]
	v_mfma_f32_16x16x32_bf16 v[82:85], v[166:169], v[208:211], v[82:85]
	v_mfma_f32_16x16x32_bf16 v[70:73], v[150:153], v[216:219], v[70:73]
	v_mfma_f32_16x16x32_bf16 v[66:69], v[166:169], v[216:219], v[66:69]
	s_setprio 0
	s_barrier
; #define PG8_STAGE(bufoff, gbase, voff) do { _Pragma("unroll") for (int _i = 0; _i < 2; ++_i) \
;         __builtin_amdgcn_global_load_lds((const unsigned*)((const char*)(gbase) + (voff)[_i]), (LAS unsigned*)(lds + (bufoff) + ldsw + _i * 8192), 16, 0, 0); } while (0)
; #define PG8_STAGE_A(bufoff, gbase, spf) do { _Pragma("unroll") for (int _i = 0; _i < 2; ++_i) \
;         __builtin_amdgcn_global_load_lds((const unsigned*)((const char*)(gbase) + (Epi::SPECIAL_ROWS && (spf) ? voffS[_i] : voffA[_i])), (LAS unsigned*)(lds + (bufoff) + ldsw + _i * 8192), 16, 0, 0); } while (0)
; #define PG8_LDA(dst, b, h) do { _Pragma("unroll") for (int m = 0; m < 4; ++m) _Pragma("unroll") for (int k = 0; k < 2; ++k) dst[m][k] = *(const LAS bf16x8*)(lds + PG8_SA(b, h) + aoff + m * 2048 + k * 1024); } while (0)
; #define PG8_MMA(ai, bj, At, Bt) do { __builtin_amdgcn_s_setprio(1); _Pragma("unroll") for (int m = 0; m < 4; ++m) _Pragma("unroll") for (int n = 0; n < 2; ++n) _Pragma("unroll") for (int k = 0; k < 2; ++k) \
;         acc[ai][bj][m][n] = __builtin_amdgcn_mfma_f32_16x16x32_bf16(Bt[n][k], At[m][k], acc[ai][bj][m][n], 0, 0, 0); __builtin_amdgcn_s_setprio(0); } while (0)
; #define PG8_WAIT_V(n) asm volatile("s_waitcnt vmcnt(" #n ")" ::: "memory")
; #define PG8_WAIT_L(n) asm volatile("s_waitcnt lgkmcnt(" #n ")" ::: "memory")
; #define PG8_BAR __builtin_amdgcn_s_barrier()
; #define PG8_SCHED __builtin_amdgcn_sched_barrier(0)
; template <class Epi>
; __device__ __forceinline__ void gemm_phase(LAS unsigned char* lds, const Gemm g, const Sched& S, const Epi& E) {
;     ...
;             PG8_LDA(At, 1, 1); PG8_STAGE(PG8_SB(1, 0), b3, voffB); PG8_STAGE(PG8_SB(1, 1), b3 + hstepB, voffB); PG8_STAGE_A(PG8_SA(1, 0), a3, sp2);
;             PG8_WAIT_V(8); PG8_WAIT_L(0); PG8_BAR; PG8_MMA(1, 0, At, B0); PG8_MMA(1, 1, At, B1); PG8_BAR; PG8_SCHED;
;         }
;         if (wr == 0) PG8_BAR;
	s_add_i32 s8, s34, s44
	v_lshl_add_u64 v[200:201], v[200:201], 0, s[20:21]
	s_mov_b32 m0, s8
	ds_read_b128 v[170:173], v180 offset:49152
	ds_read_b128 v[174:177], v180 offset:50176
	ds_read_b128 v[182:185], v180 offset:51200
	ds_read_b128 v[186:189], v180 offset:52224
	ds_read_b128 v[190:193], v180 offset:53248
	ds_read_b128 v[208:211], v180 offset:54272
	ds_read_b128 v[212:215], v180 offset:55296
	ds_read_b128 v[216:219], v180 offset:56320
	global_load_lds_dwordx4 v[200:201], off
	s_add_i32 m0, s8, 0x2000
	s_add_u32 s8, s22, 0xb0080
	v_lshl_add_u64 v[200:201], v[202:203], 0, s[20:21]
	s_addc_u32 s9, s23, 0
	s_add_i32 s22, s35, s44
	global_load_lds_dwordx4 v[200:201], off
	v_lshl_add_u64 v[200:201], s[8:9], 0, v[0:1]
	s_mov_b32 m0, s22
	s_nop 0
	global_load_lds_dwordx4 v[200:201], off
	v_lshl_add_u64 v[200:201], s[8:9], 0, v[158:159]
	s_add_i32 m0, s22, 0x2000
	s_nop 0
	global_load_lds_dwordx4 v[200:201], off
	v_lshl_add_u64 v[200:201], v[204:205], 0, s[20:21]
	s_mov_b32 m0, s56
	s_nop 0
	global_load_lds_dwordx4 v[200:201], off
	v_lshl_add_u64 v[200:201], v[206:207], 0, s[20:21]
	s_mov_b32 m0, s57
	s_nop 0
	global_load_lds_dwordx4 v[200:201], off
	s_waitcnt vmcnt(8)
	s_waitcnt lgkmcnt(0)
	s_barrier
	s_setprio 1
	s_waitcnt lgkmcnt(0)
	v_mfma_f32_16x16x32_bf16 v[62:65], v[130:133], v[170:173], v[62:65]
	v_mfma_f32_16x16x32_bf16 v[58:61], v[138:141], v[170:173], v[58:61]
	v_mfma_f32_16x16x32_bf16 v[46:49], v[130:133], v[182:185], v[46:49]
	v_mfma_f32_16x16x32_bf16 v[42:45], v[138:141], v[182:185], v[42:45]
	v_mfma_f32_16x16x32_bf16 v[30:33], v[130:133], v[190:193], v[30:33]
	v_mfma_f32_16x16x32_bf16 v[26:29], v[138:141], v[190:193], v[26:29]
	v_mfma_f32_16x16x32_bf16 v[14:17], v[130:133], v[212:215], v[14:17]
	v_mfma_f32_16x16x32_bf16 v[10:13], v[138:141], v[212:215], v[10:13]
	v_mfma_f32_16x16x32_bf16 v[62:65], v[134:137], v[174:177], v[62:65]
	v_mfma_f32_16x16x32_bf16 v[58:61], v[142:145], v[174:177], v[58:61]
	v_mfma_f32_16x16x32_bf16 v[46:49], v[134:137], v[186:189], v[46:49]
	v_mfma_f32_16x16x32_bf16 v[42:45], v[142:145], v[186:189], v[42:45]
	v_mfma_f32_16x16x32_bf16 v[30:33], v[134:137], v[208:211], v[30:33]
	v_mfma_f32_16x16x32_bf16 v[26:29], v[142:145], v[208:211], v[26:29]
	v_mfma_f32_16x16x32_bf16 v[14:17], v[134:137], v[216:219], v[14:17]
	v_mfma_f32_16x16x32_bf16 v[10:13], v[142:145], v[216:219], v[10:13]
	s_setprio 0
	s_setprio 1
	v_mfma_f32_16x16x32_bf16 v[54:57], v[146:149], v[170:173], v[54:57]
	v_mfma_f32_16x16x32_bf16 v[50:53], v[154:157], v[170:173], v[50:53]
	v_mfma_f32_16x16x32_bf16 v[38:41], v[146:149], v[182:185], v[38:41]
	v_mfma_f32_16x16x32_bf16 v[34:37], v[154:157], v[182:185], v[34:37]
	v_mfma_f32_16x16x32_bf16 v[22:25], v[146:149], v[190:193], v[22:25]
	v_mfma_f32_16x16x32_bf16 v[18:21], v[154:157], v[190:193], v[18:21]
	v_mfma_f32_16x16x32_bf16 v[6:9], v[146:149], v[212:215], v[6:9]
	v_mfma_f32_16x16x32_bf16 v[2:5], v[154:157], v[212:215], v[2:5]
	v_mfma_f32_16x16x32_bf16 v[54:57], v[150:153], v[174:177], v[54:57]
	v_mfma_f32_16x16x32_bf16 v[50:53], v[166:169], v[174:177], v[50:53]
	v_mfma_f32_16x16x32_bf16 v[38:41], v[150:153], v[186:189], v[38:41]
	v_mfma_f32_16x16x32_bf16 v[34:37], v[166:169], v[186:189], v[34:37]
	v_mfma_f32_16x16x32_bf16 v[22:25], v[150:153], v[208:211], v[22:25]
	v_mfma_f32_16x16x32_bf16 v[18:21], v[166:169], v[208:211], v[18:21]
	v_mfma_f32_16x16x32_bf16 v[6:9], v[150:153], v[216:219], v[6:9]
	v_mfma_f32_16x16x32_bf16 v[2:5], v[166:169], v[216:219], v[2:5]
	s_setprio 0
	s_barrier
	s_add_i32 s31, s31, 2
	s_add_u32 s13, s13, 0x100
	s_addc_u32 s30, s30, 0
	s_cmp_gt_u32 s31, 41
	s_mov_b64 s[34:35], s[42:43]
	s_cbranch_scc0 .LBB0_1023
	s_and_b64 vcc, exec, s[14:15]
	s_cbranch_vccz .LBB0_1026
	s_barrier
